# K-loop memory segments reordered: LDS-DMA loads (and their address prep) issued first, LDS fragment reads behind them
# speedup vs baseline: 1.0026x; 1.0010x over previous
; #define PG8_STAGE(bufoff, gbase, voff) do { _Pragma("unroll") for (int _i = 0; _i < 2; ++_i) \
;         __builtin_amdgcn_global_load_lds((const unsigned*)((const char*)(gbase) + (voff)[_i]), (LAS unsigned*)(lds + (bufoff) + ldsw + _i * 8192), 16, 0, 0); } while (0)
; #define PG8_LDA(dst, b, h) do { _Pragma("unroll") for (int m = 0; m < 4; ++m) _Pragma("unroll") for (int k = 0; k < 2; ++k) dst[m][k] = *(const LAS bf16x8*)(lds + PG8_SA(b, h) + aoff + m * 2048 + k * 1024); } while (0)
; #define PG8_LDB(dst, b, h) do { _Pragma("unroll") for (int n = 0; n < 2; ++n) _Pragma("unroll") for (int k = 0; k < 2; ++k) dst[n][k] = *(const LAS bf16x8*)(lds + PG8_SB(b, h) + boff + n * 2048 + k * 1024); } while (0)
; #define PG8_MMA(ai, bj, At, Bt) do { __builtin_amdgcn_s_setprio(1); _Pragma("unroll") for (int m = 0; m < 4; ++m) _Pragma("unroll") for (int n = 0; n < 2; ++n) _Pragma("unroll") for (int k = 0; k < 2; ++k) \
;         acc[ai][bj][m][n] = __builtin_amdgcn_mfma_f32_16x16x32_bf16(Bt[n][k], At[m][k], acc[ai][bj][m][n], 0, 0, 0); __builtin_amdgcn_s_setprio(0); } while (0)
; #define PG8_WAIT_V(n) asm volatile("s_waitcnt vmcnt(" #n ")" ::: "memory")
; #define PG8_WAIT_L(n) asm volatile("s_waitcnt lgkmcnt(" #n ")" ::: "memory")
; #define PG8_BAR __builtin_amdgcn_s_barrier()
; #define PG8_SCHED __builtin_amdgcn_sched_barrier(0)
; template <class Epi, int AMODE>
; __device__ __forceinline__ void gemm_phase(LAS unsigned char* lds, const Gemm g, const StaticOrder& S, const Epi& E, int stagger_us, int tid_in) {
;     ...
;             PG8_LDB(B0, 0, 0); PG8_LDB(B1, 0, 1); PG8_SCHED; PG8_LDA(At, 0, 0); PG8_STAGE(PG8_SA(1, 1), a1 + hstepA, voffA);
;             PG8_WAIT_V(8); PG8_WAIT_L(0); PG8_BAR; PG8_MMA(0, 0, At, B0); PG8_MMA(0, 1, At, B1); PG8_BAR; PG8_SCHED;
;             PG8_LDA(At, 0, 1); PG8_STAGE(PG8_SB(0, 0), b2, voffB); PG8_STAGE(PG8_SB(0, 1), b2 + hstepB, voffB); PG8_STAGE(PG8_SA(0, 0), a2, voffA);
;             PG8_WAIT_V(8); PG8_WAIT_L(0); PG8_BAR; PG8_MMA(1, 0, At, B0); PG8_MMA(1, 1, At, B1); PG8_BAR; PG8_SCHED;
.LBB0_396:
	s_add_u32 s4, s60, 0xfff80080
	s_addc_u32 s5, s61, -1
	s_add_i32 s30, 0, 0x10000
	s_cmp_eq_u32 s29, 28
	s_cselect_b32 s7, s27, s5
	s_cselect_b32 s6, s28, s4
	v_add_u32_e32 v140, s30, v162
	s_cselect_b32 s5, s49, vcc_hi
	s_cselect_b32 s4, s51, vcc_lo
	s_add_i32 s44, 0, 0x14000
	ds_read_b128 v[144:147], v140
	ds_read_b128 v[148:151], v140 offset:1024
	ds_read_b128 v[152:155], v140 offset:2048
	ds_read_b128 v[156:159], v140 offset:3072
	v_add_u32_e32 v140, s44, v162
	ds_read_b128 v[166:169], v140
	ds_read_b128 v[170:173], v140 offset:1024
	ds_read_b128 v[174:177], v140 offset:2048
	ds_read_b128 v[178:181], v140 offset:3072
	v_lshl_add_u64 v[140:141], s[60:61], 0, v[136:137]
	s_add_i32 m0, s57, 0xc000
	ds_read_b128 v[182:185], v164
	ds_read_b128 v[186:189], v164 offset:1024
	ds_read_b128 v[190:193], v164 offset:2048
	ds_read_b128 v[194:197], v164 offset:3072
	ds_read_b128 v[198:201], v164 offset:4096
	ds_read_b128 v[202:205], v164 offset:5120
	ds_read_b128 v[206:209], v164 offset:6144
	ds_read_b128 v[210:213], v164 offset:7168
	global_load_lds_dwordx4 v[140:141], off
	s_add_i32 m0, s57, 0xe000
	v_lshl_add_u64 v[140:141], s[60:61], 0, v[138:139]
	global_load_lds_dwordx4 v[140:141], off
	s_setprio 1
	s_waitcnt vmcnt(8) lgkmcnt(0)
	s_barrier
	v_mfma_f32_16x16x32_bf16 v[126:129], v[144:147], v[182:185], v[126:129]
	v_mfma_f32_16x16x32_bf16 v[122:125], v[152:155], v[182:185], v[122:125]
	v_mfma_f32_16x16x32_bf16 v[110:113], v[144:147], v[190:193], v[110:113]
	v_mfma_f32_16x16x32_bf16 v[106:109], v[152:155], v[190:193], v[106:109]
	v_mfma_f32_16x16x32_bf16 v[94:97], v[144:147], v[198:201], v[94:97]
	v_mfma_f32_16x16x32_bf16 v[90:93], v[152:155], v[198:201], v[90:93]
	v_mfma_f32_16x16x32_bf16 v[78:81], v[144:147], v[206:209], v[78:81]
	v_mfma_f32_16x16x32_bf16 v[74:77], v[152:155], v[206:209], v[74:77]
	v_mfma_f32_16x16x32_bf16 v[126:129], v[148:151], v[186:189], v[126:129]
	v_mfma_f32_16x16x32_bf16 v[122:125], v[156:159], v[186:189], v[122:125]
	v_mfma_f32_16x16x32_bf16 v[110:113], v[148:151], v[194:197], v[110:113]
	v_mfma_f32_16x16x32_bf16 v[106:109], v[156:159], v[194:197], v[106:109]
	v_mfma_f32_16x16x32_bf16 v[94:97], v[148:151], v[202:205], v[94:97]
	v_mfma_f32_16x16x32_bf16 v[90:93], v[156:159], v[202:205], v[90:93]
	v_mfma_f32_16x16x32_bf16 v[78:81], v[148:151], v[210:213], v[78:81]
	v_mfma_f32_16x16x32_bf16 v[74:77], v[156:159], v[210:213], v[74:77]
	v_mfma_f32_16x16x32_bf16 v[118:121], v[166:169], v[182:185], v[118:121]
	v_mfma_f32_16x16x32_bf16 v[114:117], v[174:177], v[182:185], v[114:117]
	v_mfma_f32_16x16x32_bf16 v[102:105], v[166:169], v[190:193], v[102:105]
	v_mfma_f32_16x16x32_bf16 v[98:101], v[174:177], v[190:193], v[98:101]
	v_mfma_f32_16x16x32_bf16 v[86:89], v[166:169], v[198:201], v[86:89]
	v_mfma_f32_16x16x32_bf16 v[82:85], v[174:177], v[198:201], v[82:85]
	v_mfma_f32_16x16x32_bf16 v[70:73], v[166:169], v[206:209], v[70:73]
	v_mfma_f32_16x16x32_bf16 v[66:69], v[174:177], v[206:209], v[66:69]
	v_mfma_f32_16x16x32_bf16 v[118:121], v[170:173], v[186:189], v[118:121]
	v_mfma_f32_16x16x32_bf16 v[114:117], v[178:181], v[186:189], v[114:117]
	v_mfma_f32_16x16x32_bf16 v[102:105], v[170:173], v[194:197], v[102:105]
	v_mfma_f32_16x16x32_bf16 v[98:101], v[178:181], v[194:197], v[98:101]
	v_mfma_f32_16x16x32_bf16 v[86:89], v[170:173], v[202:205], v[86:89]
	v_mfma_f32_16x16x32_bf16 v[82:85], v[178:181], v[202:205], v[82:85]
	v_mfma_f32_16x16x32_bf16 v[70:73], v[170:173], v[210:213], v[70:73]
	v_mfma_f32_16x16x32_bf16 v[66:69], v[178:181], v[210:213], v[66:69]
	s_setprio 0
	s_barrier
	s_add_i32 s30, s30, s66
	s_mov_b32 m0, s30
	v_lshl_add_u64 v[140:141], s[4:5], 0, v[0:1]
	global_load_lds_dwordx4 v[140:141], off
	s_add_i32 m0, s30, 0x2000
	s_add_u32 s30, s4, 0x80000
	v_lshl_add_u64 v[160:161], s[4:5], 0, v[130:131]
	s_addc_u32 s31, s5, 0
	s_add_i32 s44, s44, s66
	global_load_lds_dwordx4 v[160:161], off
	v_lshl_add_u64 v[214:215], s[30:31], 0, v[0:1]
	s_mov_b32 m0, s44
	v_lshl_add_u64 v[216:217], s[6:7], 0, v[132:133]
	global_load_lds_dwordx4 v[214:215], off
	s_add_i32 m0, s44, 0x2000
	v_lshl_add_u64 v[214:215], s[30:31], 0, v[130:131]
	global_load_lds_dwordx4 v[214:215], off
	s_mov_b32 m0, s57
	v_lshl_add_u64 v[214:215], s[6:7], 0, v[134:135]
	global_load_lds_dwordx4 v[214:215], off
	s_mov_b32 m0, s59
	s_nop 0
	global_load_lds_dwordx4 v[216:217], off
	ds_read_b128 v[182:185], v164 offset:16384
	ds_read_b128 v[186:189], v164 offset:17408
	ds_read_b128 v[190:193], v164 offset:18432
	ds_read_b128 v[194:197], v164 offset:19456
	ds_read_b128 v[198:201], v164 offset:20480
	ds_read_b128 v[202:205], v164 offset:21504
	ds_read_b128 v[206:209], v164 offset:22528
	ds_read_b128 v[210:213], v164 offset:23552
	s_setprio 1
	s_waitcnt vmcnt(8) lgkmcnt(0)
	s_barrier
; #define PG8_STAGE(bufoff, gbase, voff) do { _Pragma("unroll") for (int _i = 0; _i < 2; ++_i) \
;         __builtin_amdgcn_global_load_lds((const unsigned*)((const char*)(gbase) + (voff)[_i]), (LAS unsigned*)(lds + (bufoff) + ldsw + _i * 8192), 16, 0, 0); } while (0)
; #define PG8_LDA(dst, b, h) do { _Pragma("unroll") for (int m = 0; m < 4; ++m) _Pragma("unroll") for (int k = 0; k < 2; ++k) dst[m][k] = *(const LAS bf16x8*)(lds + PG8_SA(b, h) + aoff + m * 2048 + k * 1024); } while (0)
; #define PG8_LDB(dst, b, h) do { _Pragma("unroll") for (int n = 0; n < 2; ++n) _Pragma("unroll") for (int k = 0; k < 2; ++k) dst[n][k] = *(const LAS bf16x8*)(lds + PG8_SB(b, h) + boff + n * 2048 + k * 1024); } while (0)
; #define PG8_MMA(ai, bj, At, Bt) do { __builtin_amdgcn_s_setprio(1); _Pragma("unroll") for (int m = 0; m < 4; ++m) _Pragma("unroll") for (int n = 0; n < 2; ++n) _Pragma("unroll") for (int k = 0; k < 2; ++k) \
;         acc[ai][bj][m][n] = __builtin_amdgcn_mfma_f32_16x16x32_bf16(Bt[n][k], At[m][k], acc[ai][bj][m][n], 0, 0, 0); __builtin_amdgcn_s_setprio(0); } while (0)
; #define PG8_WAIT_V(n) asm volatile("s_waitcnt vmcnt(" #n ")" ::: "memory")
; #define PG8_WAIT_L(n) asm volatile("s_waitcnt lgkmcnt(" #n ")" ::: "memory")
; #define PG8_BAR __builtin_amdgcn_s_barrier()
; #define PG8_SCHED __builtin_amdgcn_sched_barrier(0)
; template <class Epi, int AMODE>
; __device__ __forceinline__ void gemm_phase(LAS unsigned char* lds, const Gemm g, const StaticOrder& S, const Epi& E, int stagger_us, int tid_in) {
;     ...
;             PG8_WAIT_V(8); PG8_WAIT_L(0); PG8_BAR; PG8_MMA(1, 0, At, B0); PG8_MMA(1, 1, At, B1); PG8_BAR; PG8_SCHED;
;             PG8_LDB(B0, 1, 0); PG8_LDB(B1, 1, 1); PG8_SCHED; PG8_LDA(At, 1, 0); PG8_STAGE(PG8_SA(0, 1), a2 + hstepA, voffA);
;             PG8_WAIT_V(8); PG8_WAIT_L(0); PG8_BAR; PG8_MMA(0, 0, At, B0); PG8_MMA(0, 1, At, B1); PG8_BAR; PG8_SCHED;
	v_mfma_f32_16x16x32_bf16 v[62:65], v[144:147], v[182:185], v[62:65]
	v_mfma_f32_16x16x32_bf16 v[58:61], v[152:155], v[182:185], v[58:61]
	v_mfma_f32_16x16x32_bf16 v[46:49], v[144:147], v[190:193], v[46:49]
	v_mfma_f32_16x16x32_bf16 v[42:45], v[152:155], v[190:193], v[42:45]
	v_mfma_f32_16x16x32_bf16 v[30:33], v[144:147], v[198:201], v[30:33]
	v_mfma_f32_16x16x32_bf16 v[26:29], v[152:155], v[198:201], v[26:29]
	v_mfma_f32_16x16x32_bf16 v[14:17], v[144:147], v[206:209], v[14:17]
	v_mfma_f32_16x16x32_bf16 v[10:13], v[152:155], v[206:209], v[10:13]
	v_mfma_f32_16x16x32_bf16 v[62:65], v[148:151], v[186:189], v[62:65]
	v_mfma_f32_16x16x32_bf16 v[58:61], v[156:159], v[186:189], v[58:61]
	v_mfma_f32_16x16x32_bf16 v[46:49], v[148:151], v[194:197], v[46:49]
	v_mfma_f32_16x16x32_bf16 v[42:45], v[156:159], v[194:197], v[42:45]
	v_mfma_f32_16x16x32_bf16 v[30:33], v[148:151], v[202:205], v[30:33]
	v_mfma_f32_16x16x32_bf16 v[26:29], v[156:159], v[202:205], v[26:29]
	v_mfma_f32_16x16x32_bf16 v[14:17], v[148:151], v[210:213], v[14:17]
	v_mfma_f32_16x16x32_bf16 v[10:13], v[156:159], v[210:213], v[10:13]
	v_mfma_f32_16x16x32_bf16 v[54:57], v[166:169], v[182:185], v[54:57]
	v_mfma_f32_16x16x32_bf16 v[50:53], v[174:177], v[182:185], v[50:53]
	v_mfma_f32_16x16x32_bf16 v[38:41], v[166:169], v[190:193], v[38:41]
	v_mfma_f32_16x16x32_bf16 v[34:37], v[174:177], v[190:193], v[34:37]
	v_mfma_f32_16x16x32_bf16 v[22:25], v[166:169], v[198:201], v[22:25]
	v_mfma_f32_16x16x32_bf16 v[18:21], v[174:177], v[198:201], v[18:21]
	v_mfma_f32_16x16x32_bf16 v[6:9], v[166:169], v[206:209], v[6:9]
	v_mfma_f32_16x16x32_bf16 v[2:5], v[174:177], v[206:209], v[2:5]
	v_mfma_f32_16x16x32_bf16 v[54:57], v[170:173], v[186:189], v[54:57]
	v_mfma_f32_16x16x32_bf16 v[50:53], v[178:181], v[186:189], v[50:53]
	v_mfma_f32_16x16x32_bf16 v[38:41], v[170:173], v[194:197], v[38:41]
	v_mfma_f32_16x16x32_bf16 v[34:37], v[178:181], v[194:197], v[34:37]
	v_mfma_f32_16x16x32_bf16 v[22:25], v[170:173], v[202:205], v[22:25]
	v_mfma_f32_16x16x32_bf16 v[18:21], v[178:181], v[202:205], v[18:21]
	v_mfma_f32_16x16x32_bf16 v[6:9], v[170:173], v[210:213], v[6:9]
	v_mfma_f32_16x16x32_bf16 v[2:5], v[178:181], v[210:213], v[2:5]
	s_setprio 0
	s_barrier
	s_add_u32 s6, s6, 0x80000
	s_addc_u32 s7, s7, 0
	s_mov_b32 m0, s87
	v_lshl_add_u64 v[218:219], s[6:7], 0, v[134:135]
	global_load_lds_dwordx4 v[218:219], off
	s_mov_b32 m0, s91
	v_lshl_add_u64 v[218:219], s[6:7], 0, v[132:133]
	global_load_lds_dwordx4 v[218:219], off
	s_add_i32 s30, 0, 0x18000
	v_add_u32_e32 v142, s30, v162
	s_add_i32 s31, 0, 0x1c000
	ds_read_b128 v[144:147], v142
	ds_read_b128 v[148:151], v142 offset:1024
	ds_read_b128 v[152:155], v142 offset:2048
	ds_read_b128 v[156:159], v142 offset:3072
	v_add_u32_e32 v142, s31, v162
	ds_read_b128 v[166:169], v142
	ds_read_b128 v[170:173], v142 offset:1024
	ds_read_b128 v[174:177], v142 offset:2048
	ds_read_b128 v[178:181], v142 offset:3072
	ds_read_b128 v[182:185], v164 offset:32768
	ds_read_b128 v[186:189], v164 offset:33792
	ds_read_b128 v[190:193], v164 offset:34816
	ds_read_b128 v[194:197], v164 offset:35840
	ds_read_b128 v[198:201], v164 offset:36864
	ds_read_b128 v[202:205], v164 offset:37888
	ds_read_b128 v[206:209], v164 offset:38912
	ds_read_b128 v[210:213], v164 offset:39936
	s_setprio 1
	s_waitcnt vmcnt(8) lgkmcnt(0)
	s_barrier
	v_mfma_f32_16x16x32_bf16 v[126:129], v[144:147], v[182:185], v[126:129]
	v_mfma_f32_16x16x32_bf16 v[122:125], v[152:155], v[182:185], v[122:125]
	v_mfma_f32_16x16x32_bf16 v[110:113], v[144:147], v[190:193], v[110:113]
	v_mfma_f32_16x16x32_bf16 v[106:109], v[152:155], v[190:193], v[106:109]
	v_mfma_f32_16x16x32_bf16 v[94:97], v[144:147], v[198:201], v[94:97]
	v_mfma_f32_16x16x32_bf16 v[90:93], v[152:155], v[198:201], v[90:93]
	v_mfma_f32_16x16x32_bf16 v[78:81], v[144:147], v[206:209], v[78:81]
	v_mfma_f32_16x16x32_bf16 v[74:77], v[152:155], v[206:209], v[74:77]
	v_mfma_f32_16x16x32_bf16 v[126:129], v[148:151], v[186:189], v[126:129]
	v_mfma_f32_16x16x32_bf16 v[122:125], v[156:159], v[186:189], v[122:125]
	v_mfma_f32_16x16x32_bf16 v[110:113], v[148:151], v[194:197], v[110:113]
	v_mfma_f32_16x16x32_bf16 v[106:109], v[156:159], v[194:197], v[106:109]
	v_mfma_f32_16x16x32_bf16 v[94:97], v[148:151], v[202:205], v[94:97]
	v_mfma_f32_16x16x32_bf16 v[90:93], v[156:159], v[202:205], v[90:93]
	v_mfma_f32_16x16x32_bf16 v[78:81], v[148:151], v[210:213], v[78:81]
	v_mfma_f32_16x16x32_bf16 v[74:77], v[156:159], v[210:213], v[74:77]
	v_mfma_f32_16x16x32_bf16 v[118:121], v[166:169], v[182:185], v[118:121]
	v_mfma_f32_16x16x32_bf16 v[114:117], v[174:177], v[182:185], v[114:117]
	v_mfma_f32_16x16x32_bf16 v[102:105], v[166:169], v[190:193], v[102:105]
	v_mfma_f32_16x16x32_bf16 v[98:101], v[174:177], v[190:193], v[98:101]
	v_mfma_f32_16x16x32_bf16 v[86:89], v[166:169], v[198:201], v[86:89]
	v_mfma_f32_16x16x32_bf16 v[82:85], v[174:177], v[198:201], v[82:85]
	v_mfma_f32_16x16x32_bf16 v[70:73], v[166:169], v[206:209], v[70:73]
	v_mfma_f32_16x16x32_bf16 v[66:69], v[174:177], v[206:209], v[66:69]
	v_mfma_f32_16x16x32_bf16 v[118:121], v[170:173], v[186:189], v[118:121]
	v_mfma_f32_16x16x32_bf16 v[114:117], v[178:181], v[186:189], v[114:117]
	v_mfma_f32_16x16x32_bf16 v[102:105], v[170:173], v[194:197], v[102:105]
	v_mfma_f32_16x16x32_bf16 v[98:101], v[178:181], v[194:197], v[98:101]
	v_mfma_f32_16x16x32_bf16 v[86:89], v[170:173], v[202:205], v[86:89]
	v_mfma_f32_16x16x32_bf16 v[82:85], v[178:181], v[202:205], v[82:85]
	v_mfma_f32_16x16x32_bf16 v[70:73], v[170:173], v[210:213], v[70:73]
	v_mfma_f32_16x16x32_bf16 v[66:69], v[178:181], v[210:213], v[66:69]
	s_setprio 0
	s_barrier
; #define PG8_STAGE(bufoff, gbase, voff) do { _Pragma("unroll") for (int _i = 0; _i < 2; ++_i) \
;         __builtin_amdgcn_global_load_lds((const unsigned*)((const char*)(gbase) + (voff)[_i]), (LAS unsigned*)(lds + (bufoff) + ldsw + _i * 8192), 16, 0, 0); } while (0)
; #define PG8_LDA(dst, b, h) do { _Pragma("unroll") for (int m = 0; m < 4; ++m) _Pragma("unroll") for (int k = 0; k < 2; ++k) dst[m][k] = *(const LAS bf16x8*)(lds + PG8_SA(b, h) + aoff + m * 2048 + k * 1024); } while (0)
; #define PG8_MMA(ai, bj, At, Bt) do { __builtin_amdgcn_s_setprio(1); _Pragma("unroll") for (int m = 0; m < 4; ++m) _Pragma("unroll") for (int n = 0; n < 2; ++n) _Pragma("unroll") for (int k = 0; k < 2; ++k) \
;         acc[ai][bj][m][n] = __builtin_amdgcn_mfma_f32_16x16x32_bf16(Bt[n][k], At[m][k], acc[ai][bj][m][n], 0, 0, 0); __builtin_amdgcn_s_setprio(0); } while (0)
; #define PG8_WAIT_V(n) asm volatile("s_waitcnt vmcnt(" #n ")" ::: "memory")
; #define PG8_WAIT_L(n) asm volatile("s_waitcnt lgkmcnt(" #n ")" ::: "memory")
; #define PG8_BAR __builtin_amdgcn_s_barrier()
; #define PG8_SCHED __builtin_amdgcn_sched_barrier(0)
; template <class Epi, int AMODE>
; __device__ __forceinline__ void gemm_phase(LAS unsigned char* lds, const Gemm g, const StaticOrder& S, const Epi& E, int stagger_us, int tid_in) {
;     ...
;             PG8_LDA(At, 1, 1); PG8_STAGE(PG8_SB(1, 0), b3, voffB); PG8_STAGE(PG8_SB(1, 1), b3 + hstepB, voffB); PG8_STAGE(PG8_SA(1, 0), a3, voffA);
;             PG8_WAIT_V(8); PG8_WAIT_L(0); PG8_BAR; PG8_MMA(1, 0, At, B0); PG8_MMA(1, 1, At, B1); PG8_BAR; PG8_SCHED;
;         }
;         if (wr == 0) PG8_BAR;
	s_add_i32 s6, s30, s66
	s_mov_b32 m0, s6
	v_lshl_add_u64 v[140:141], v[140:141], 0, s[74:75]
	global_load_lds_dwordx4 v[140:141], off
	s_add_i32 m0, s6, 0x2000
	s_add_u32 s4, s4, 0x80080
	v_lshl_add_u64 v[140:141], v[160:161], 0, s[74:75]
	s_addc_u32 s5, s5, 0
	s_add_i32 s6, s31, s66
	global_load_lds_dwordx4 v[140:141], off
	s_mov_b32 m0, s6
	v_lshl_add_u64 v[140:141], s[4:5], 0, v[0:1]
	global_load_lds_dwordx4 v[140:141], off
	s_add_i32 m0, s6, 0x2000
	v_lshl_add_u64 v[140:141], s[4:5], 0, v[130:131]
	global_load_lds_dwordx4 v[140:141], off
	s_mov_b32 m0, s95
	v_lshl_add_u64 v[140:141], v[214:215], 0, s[74:75]
	global_load_lds_dwordx4 v[140:141], off
	s_mov_b32 m0, s96
	v_lshl_add_u64 v[140:141], v[216:217], 0, s[74:75]
	global_load_lds_dwordx4 v[140:141], off
	ds_read_b128 v[182:185], v164 offset:49152
	ds_read_b128 v[186:189], v164 offset:50176
	ds_read_b128 v[190:193], v164 offset:51200
	ds_read_b128 v[194:197], v164 offset:52224
	ds_read_b128 v[198:201], v164 offset:53248
	ds_read_b128 v[202:205], v164 offset:54272
	ds_read_b128 v[206:209], v164 offset:55296
	ds_read_b128 v[210:213], v164 offset:56320
	s_setprio 1
	s_waitcnt vmcnt(8) lgkmcnt(0)
	s_barrier
	v_mfma_f32_16x16x32_bf16 v[62:65], v[144:147], v[182:185], v[62:65]
	v_mfma_f32_16x16x32_bf16 v[58:61], v[152:155], v[182:185], v[58:61]
	v_mfma_f32_16x16x32_bf16 v[46:49], v[144:147], v[190:193], v[46:49]
	v_mfma_f32_16x16x32_bf16 v[42:45], v[152:155], v[190:193], v[42:45]
	v_mfma_f32_16x16x32_bf16 v[30:33], v[144:147], v[198:201], v[30:33]
	v_mfma_f32_16x16x32_bf16 v[26:29], v[152:155], v[198:201], v[26:29]
	v_mfma_f32_16x16x32_bf16 v[14:17], v[144:147], v[206:209], v[14:17]
	v_mfma_f32_16x16x32_bf16 v[10:13], v[152:155], v[206:209], v[10:13]
	v_mfma_f32_16x16x32_bf16 v[62:65], v[148:151], v[186:189], v[62:65]
	v_mfma_f32_16x16x32_bf16 v[58:61], v[156:159], v[186:189], v[58:61]
	v_mfma_f32_16x16x32_bf16 v[46:49], v[148:151], v[194:197], v[46:49]
	v_mfma_f32_16x16x32_bf16 v[42:45], v[156:159], v[194:197], v[42:45]
	v_mfma_f32_16x16x32_bf16 v[30:33], v[148:151], v[202:205], v[30:33]
	v_mfma_f32_16x16x32_bf16 v[26:29], v[156:159], v[202:205], v[26:29]
	v_mfma_f32_16x16x32_bf16 v[14:17], v[148:151], v[210:213], v[14:17]
	v_mfma_f32_16x16x32_bf16 v[10:13], v[156:159], v[210:213], v[10:13]
	v_mfma_f32_16x16x32_bf16 v[54:57], v[166:169], v[182:185], v[54:57]
	v_mfma_f32_16x16x32_bf16 v[50:53], v[174:177], v[182:185], v[50:53]
	v_mfma_f32_16x16x32_bf16 v[38:41], v[166:169], v[190:193], v[38:41]
	v_mfma_f32_16x16x32_bf16 v[34:37], v[174:177], v[190:193], v[34:37]
	v_mfma_f32_16x16x32_bf16 v[22:25], v[166:169], v[198:201], v[22:25]
	v_mfma_f32_16x16x32_bf16 v[18:21], v[174:177], v[198:201], v[18:21]
	v_mfma_f32_16x16x32_bf16 v[6:9], v[166:169], v[206:209], v[6:9]
	v_mfma_f32_16x16x32_bf16 v[2:5], v[174:177], v[206:209], v[2:5]
	v_mfma_f32_16x16x32_bf16 v[54:57], v[170:173], v[186:189], v[54:57]
	v_mfma_f32_16x16x32_bf16 v[50:53], v[178:181], v[186:189], v[50:53]
	v_mfma_f32_16x16x32_bf16 v[38:41], v[170:173], v[194:197], v[38:41]
	v_mfma_f32_16x16x32_bf16 v[34:37], v[178:181], v[194:197], v[34:37]
	v_mfma_f32_16x16x32_bf16 v[22:25], v[170:173], v[202:205], v[22:25]
	v_mfma_f32_16x16x32_bf16 v[18:21], v[178:181], v[202:205], v[18:21]
	v_mfma_f32_16x16x32_bf16 v[6:9], v[170:173], v[210:213], v[6:9]
	v_mfma_f32_16x16x32_bf16 v[2:5], v[178:181], v[210:213], v[2:5]
	s_setprio 0
	s_barrier
	s_add_i32 s29, s29, 2
	s_add_u32 s60, s60, 0x100
	s_addc_u32 s61, s61, 0
	s_add_u32 vcc_lo, vcc_lo, 0x100
	s_addc_u32 vcc_hi, vcc_hi, 0
	s_cmp_gt_u32 s29, 29
	s_cbranch_scc0 .LBB0_396
	s_and_b64 vcc, exec, s[46:47]
	s_cbranch_vccz .LBB0_399
	s_barrier

; #define PG8_STAGE(bufoff, gbase, voff) do { _Pragma("unroll") for (int _i = 0; _i < 2; ++_i) \
;         __builtin_amdgcn_global_load_lds((const unsigned*)((const char*)(gbase) + (voff)[_i]), (LAS unsigned*)(lds + (bufoff) + ldsw + _i * 8192), 16, 0, 0); } while (0)
; #define PG8_LDA(dst, b, h) do { _Pragma("unroll") for (int m = 0; m < 4; ++m) _Pragma("unroll") for (int k = 0; k < 2; ++k) dst[m][k] = *(const LAS bf16x8*)(lds + PG8_SA(b, h) + aoff + m * 2048 + k * 1024); } while (0)
; #define PG8_LDB(dst, b, h) do { _Pragma("unroll") for (int n = 0; n < 2; ++n) _Pragma("unroll") for (int k = 0; k < 2; ++k) dst[n][k] = *(const LAS bf16x8*)(lds + PG8_SB(b, h) + boff + n * 2048 + k * 1024); } while (0)
; #define PG8_MMA(ai, bj, At, Bt) do { __builtin_amdgcn_s_setprio(1); _Pragma("unroll") for (int m = 0; m < 4; ++m) _Pragma("unroll") for (int n = 0; n < 2; ++n) _Pragma("unroll") for (int k = 0; k < 2; ++k) \
;         acc[ai][bj][m][n] = __builtin_amdgcn_mfma_f32_16x16x32_bf16(Bt[n][k], At[m][k], acc[ai][bj][m][n], 0, 0, 0); __builtin_amdgcn_s_setprio(0); } while (0)
; #define PG8_WAIT_V(n) asm volatile("s_waitcnt vmcnt(" #n ")" ::: "memory")
; #define PG8_WAIT_L(n) asm volatile("s_waitcnt lgkmcnt(" #n ")" ::: "memory")
; #define PG8_BAR __builtin_amdgcn_s_barrier()
; #define PG8_SCHED __builtin_amdgcn_sched_barrier(0)
; template <class Epi, int AMODE>
; __device__ __forceinline__ void gemm_phase(LAS unsigned char* lds, const Gemm g, const StaticOrder& S, const Epi& E, int stagger_us, int tid_in) {
;     ...
;             PG8_LDB(B0, 0, 0); PG8_LDB(B1, 0, 1); PG8_SCHED; PG8_LDA(At, 0, 0); PG8_STAGE(PG8_SA(1, 1), a1 + hstepA, voffA);
;             PG8_WAIT_V(8); PG8_WAIT_L(0); PG8_BAR; PG8_MMA(0, 0, At, B0); PG8_MMA(0, 1, At, B1); PG8_BAR; PG8_SCHED;
;             PG8_LDA(At, 0, 1); PG8_STAGE(PG8_SB(0, 0), b2, voffB); PG8_STAGE(PG8_SB(0, 1), b2 + hstepB, voffB); PG8_STAGE(PG8_SA(0, 0), a2, voffA);
;             PG8_WAIT_V(8); PG8_WAIT_L(0); PG8_BAR; PG8_MMA(1, 0, At, B0); PG8_MMA(1, 1, At, B1); PG8_BAR; PG8_SCHED;
.LBB0_1199:
	s_add_i32 m0, s66, 0xc000
	v_lshl_add_u64 v[200:201], s[46:47], 0, v[176:177]
	global_load_lds_dwordx4 v[200:201], off
	s_add_i32 m0, s66, 0xe000
	v_lshl_add_u64 v[200:201], s[46:47], 0, v[178:179]
	global_load_lds_dwordx4 v[200:201], off
	s_add_u32 s4, s46, 0x100
	s_addc_u32 s5, s47, 0
	s_add_i32 s34, 0, 0x10000
	s_cmp_eq_u32 s31, 28
	s_cselect_b32 s95, s61, s5
	s_cselect_b32 s94, vcc_lo, s4
	s_cselect_b32 s7, s59, s30
	s_cselect_b32 s6, vcc_hi, s29
	s_add_i32 s35, 0, 0x14000
	v_add_u32_e32 v62, s34, v205
	v_add_u32_e32 v158, s35, v205
	ds_read_b128 v[50:53], v62
	ds_read_b128 v[54:57], v62 offset:1024
	ds_read_b128 v[58:61], v62 offset:2048
	ds_read_b128 v[62:65], v62 offset:3072
	ds_read_b128 v[146:149], v158
	ds_read_b128 v[150:153], v158 offset:1024
	ds_read_b128 v[154:157], v158 offset:2048
	ds_read_b128 v[158:161], v158 offset:3072
	ds_read_b128 v[162:165], v207
	ds_read_b128 v[166:169], v207 offset:1024
	ds_read_b128 v[170:173], v207 offset:2048
	ds_read_b128 v[180:183], v207 offset:3072
	ds_read_b128 v[184:187], v207 offset:4096
	ds_read_b128 v[188:191], v207 offset:5120
	ds_read_b128 v[192:195], v207 offset:6144
	ds_read_b128 v[196:199], v207 offset:7168
	s_setprio 1
	s_waitcnt vmcnt(8) lgkmcnt(0)
	s_barrier
	v_mfma_f32_16x16x32_bf16 v[142:145], v[50:53], v[162:165], v[142:145]
	v_mfma_f32_16x16x32_bf16 v[138:141], v[58:61], v[162:165], v[138:141]
	v_mfma_f32_16x16x32_bf16 v[126:129], v[50:53], v[170:173], v[126:129]
	v_mfma_f32_16x16x32_bf16 v[122:125], v[58:61], v[170:173], v[122:125]
	v_mfma_f32_16x16x32_bf16 v[110:113], v[50:53], v[184:187], v[110:113]
	v_mfma_f32_16x16x32_bf16 v[106:109], v[58:61], v[184:187], v[106:109]
	v_mfma_f32_16x16x32_bf16 v[94:97], v[50:53], v[192:195], v[94:97]
	v_mfma_f32_16x16x32_bf16 v[90:93], v[58:61], v[192:195], v[90:93]
	v_mfma_f32_16x16x32_bf16 v[142:145], v[54:57], v[166:169], v[142:145]
	v_mfma_f32_16x16x32_bf16 v[138:141], v[62:65], v[166:169], v[138:141]
	v_mfma_f32_16x16x32_bf16 v[126:129], v[54:57], v[180:183], v[126:129]
	v_mfma_f32_16x16x32_bf16 v[122:125], v[62:65], v[180:183], v[122:125]
	v_mfma_f32_16x16x32_bf16 v[110:113], v[54:57], v[188:191], v[110:113]
	v_mfma_f32_16x16x32_bf16 v[106:109], v[62:65], v[188:191], v[106:109]
	v_mfma_f32_16x16x32_bf16 v[94:97], v[54:57], v[196:199], v[94:97]
	v_mfma_f32_16x16x32_bf16 v[90:93], v[62:65], v[196:199], v[90:93]
	v_mfma_f32_16x16x32_bf16 v[134:137], v[146:149], v[162:165], v[134:137]
	v_mfma_f32_16x16x32_bf16 v[130:133], v[154:157], v[162:165], v[130:133]
	v_mfma_f32_16x16x32_bf16 v[118:121], v[146:149], v[170:173], v[118:121]
	v_mfma_f32_16x16x32_bf16 v[114:117], v[154:157], v[170:173], v[114:117]
	v_mfma_f32_16x16x32_bf16 v[102:105], v[146:149], v[184:187], v[102:105]
	v_mfma_f32_16x16x32_bf16 v[98:101], v[154:157], v[184:187], v[98:101]
	v_mfma_f32_16x16x32_bf16 v[86:89], v[146:149], v[192:195], v[86:89]
	v_mfma_f32_16x16x32_bf16 v[82:85], v[154:157], v[192:195], v[82:85]
	v_mfma_f32_16x16x32_bf16 v[134:137], v[150:153], v[166:169], v[134:137]
	v_mfma_f32_16x16x32_bf16 v[130:133], v[158:161], v[166:169], v[130:133]
	v_mfma_f32_16x16x32_bf16 v[118:121], v[150:153], v[180:183], v[118:121]
	v_mfma_f32_16x16x32_bf16 v[114:117], v[158:161], v[180:183], v[114:117]
	v_mfma_f32_16x16x32_bf16 v[102:105], v[150:153], v[188:191], v[102:105]
	v_mfma_f32_16x16x32_bf16 v[98:101], v[158:161], v[188:191], v[98:101]
	v_mfma_f32_16x16x32_bf16 v[86:89], v[150:153], v[196:199], v[86:89]
	v_mfma_f32_16x16x32_bf16 v[82:85], v[158:161], v[196:199], v[82:85]
	s_setprio 0
	s_barrier
	s_add_i32 s34, s34, s13
	s_mov_b32 m0, s34
	v_lshl_add_u64 v[200:201], s[6:7], 0, v[0:1]
	global_load_lds_dwordx4 v[200:201], off
	s_add_i32 m0, s34, 0x2000
	s_add_u32 s46, s6, 0x80000
	v_lshl_add_u64 v[202:203], s[6:7], 0, v[174:175]
	s_addc_u32 s47, s7, 0
	s_add_i32 s34, s35, s13
	global_load_lds_dwordx4 v[202:203], off
	v_lshl_add_u64 v[208:209], s[46:47], 0, v[0:1]
	s_mov_b32 m0, s34
	v_lshl_add_u64 v[210:211], s[94:95], 0, v[174:175]
	global_load_lds_dwordx4 v[208:209], off
	s_add_i32 m0, s34, 0x2000
	v_lshl_add_u64 v[208:209], s[46:47], 0, v[174:175]
	global_load_lds_dwordx4 v[208:209], off
	s_mov_b32 m0, s66
	v_lshl_add_u64 v[208:209], s[94:95], 0, v[0:1]
	global_load_lds_dwordx4 v[208:209], off
	s_mov_b32 m0, s67
	s_nop 0
	global_load_lds_dwordx4 v[210:211], off
	ds_read_b128 v[162:165], v207 offset:16384
	ds_read_b128 v[166:169], v207 offset:17408
	ds_read_b128 v[170:173], v207 offset:18432
	ds_read_b128 v[180:183], v207 offset:19456
	ds_read_b128 v[184:187], v207 offset:20480
	ds_read_b128 v[188:191], v207 offset:21504
	ds_read_b128 v[192:195], v207 offset:22528
	ds_read_b128 v[196:199], v207 offset:23552
	s_setprio 1
	s_waitcnt vmcnt(8) lgkmcnt(0)
	s_barrier
; #define PG8_STAGE(bufoff, gbase, voff) do { _Pragma("unroll") for (int _i = 0; _i < 2; ++_i) \
;         __builtin_amdgcn_global_load_lds((const unsigned*)((const char*)(gbase) + (voff)[_i]), (LAS unsigned*)(lds + (bufoff) + ldsw + _i * 8192), 16, 0, 0); } while (0)
; #define PG8_LDA(dst, b, h) do { _Pragma("unroll") for (int m = 0; m < 4; ++m) _Pragma("unroll") for (int k = 0; k < 2; ++k) dst[m][k] = *(const LAS bf16x8*)(lds + PG8_SA(b, h) + aoff + m * 2048 + k * 1024); } while (0)
; #define PG8_LDB(dst, b, h) do { _Pragma("unroll") for (int n = 0; n < 2; ++n) _Pragma("unroll") for (int k = 0; k < 2; ++k) dst[n][k] = *(const LAS bf16x8*)(lds + PG8_SB(b, h) + boff + n * 2048 + k * 1024); } while (0)
; #define PG8_MMA(ai, bj, At, Bt) do { __builtin_amdgcn_s_setprio(1); _Pragma("unroll") for (int m = 0; m < 4; ++m) _Pragma("unroll") for (int n = 0; n < 2; ++n) _Pragma("unroll") for (int k = 0; k < 2; ++k) \
;         acc[ai][bj][m][n] = __builtin_amdgcn_mfma_f32_16x16x32_bf16(Bt[n][k], At[m][k], acc[ai][bj][m][n], 0, 0, 0); __builtin_amdgcn_s_setprio(0); } while (0)
; #define PG8_WAIT_V(n) asm volatile("s_waitcnt vmcnt(" #n ")" ::: "memory")
; #define PG8_WAIT_L(n) asm volatile("s_waitcnt lgkmcnt(" #n ")" ::: "memory")
; #define PG8_BAR __builtin_amdgcn_s_barrier()
; #define PG8_SCHED __builtin_amdgcn_sched_barrier(0)
; template <class Epi, int AMODE>
; __device__ __forceinline__ void gemm_phase(LAS unsigned char* lds, const Gemm g, const StaticOrder& S, const Epi& E, int stagger_us, int tid_in) {
;     ...
;             PG8_WAIT_V(8); PG8_WAIT_L(0); PG8_BAR; PG8_MMA(1, 0, At, B0); PG8_MMA(1, 1, At, B1); PG8_BAR; PG8_SCHED;
;             PG8_LDB(B0, 1, 0); PG8_LDB(B1, 1, 1); PG8_SCHED; PG8_LDA(At, 1, 0); PG8_STAGE(PG8_SA(0, 1), a2 + hstepA, voffA);
;             PG8_WAIT_V(8); PG8_WAIT_L(0); PG8_BAR; PG8_MMA(0, 0, At, B0); PG8_MMA(0, 1, At, B1); PG8_BAR; PG8_SCHED;
	v_mfma_f32_16x16x32_bf16 v[78:81], v[50:53], v[162:165], v[78:81]
	v_mfma_f32_16x16x32_bf16 v[74:77], v[58:61], v[162:165], v[74:77]
	v_mfma_f32_16x16x32_bf16 v[46:49], v[50:53], v[170:173], v[46:49]
	v_mfma_f32_16x16x32_bf16 v[42:45], v[58:61], v[170:173], v[42:45]
	v_mfma_f32_16x16x32_bf16 v[30:33], v[50:53], v[184:187], v[30:33]
	v_mfma_f32_16x16x32_bf16 v[26:29], v[58:61], v[184:187], v[26:29]
	v_mfma_f32_16x16x32_bf16 v[14:17], v[50:53], v[192:195], v[14:17]
	v_mfma_f32_16x16x32_bf16 v[10:13], v[58:61], v[192:195], v[10:13]
	v_mfma_f32_16x16x32_bf16 v[78:81], v[54:57], v[166:169], v[78:81]
	v_mfma_f32_16x16x32_bf16 v[74:77], v[62:65], v[166:169], v[74:77]
	v_mfma_f32_16x16x32_bf16 v[46:49], v[54:57], v[180:183], v[46:49]
	v_mfma_f32_16x16x32_bf16 v[42:45], v[62:65], v[180:183], v[42:45]
	v_mfma_f32_16x16x32_bf16 v[30:33], v[54:57], v[188:191], v[30:33]
	v_mfma_f32_16x16x32_bf16 v[26:29], v[62:65], v[188:191], v[26:29]
	v_mfma_f32_16x16x32_bf16 v[14:17], v[54:57], v[196:199], v[14:17]
	v_mfma_f32_16x16x32_bf16 v[10:13], v[62:65], v[196:199], v[10:13]
	v_mfma_f32_16x16x32_bf16 v[38:41], v[146:149], v[170:173], v[38:41]
	v_mfma_f32_16x16x32_bf16 v[34:37], v[154:157], v[170:173], v[34:37]
	v_mfma_f32_16x16x32_bf16 v[22:25], v[146:149], v[184:187], v[22:25]
	v_mfma_f32_16x16x32_bf16 v[18:21], v[154:157], v[184:187], v[18:21]
	v_mfma_f32_16x16x32_bf16 v[6:9], v[146:149], v[192:195], v[6:9]
	v_mfma_f32_16x16x32_bf16 v[2:5], v[154:157], v[192:195], v[2:5]
	v_mfma_f32_16x16x32_bf16 v[50:53], v[146:149], v[162:165], v[70:73]
	v_mfma_f32_16x16x32_bf16 v[54:57], v[154:157], v[162:165], v[66:69]
	v_mfma_f32_16x16x32_bf16 v[38:41], v[150:153], v[180:183], v[38:41]
	v_mfma_f32_16x16x32_bf16 v[34:37], v[158:161], v[180:183], v[34:37]
	v_mfma_f32_16x16x32_bf16 v[22:25], v[150:153], v[188:191], v[22:25]
	v_mfma_f32_16x16x32_bf16 v[18:21], v[158:161], v[188:191], v[18:21]
	v_mfma_f32_16x16x32_bf16 v[6:9], v[150:153], v[196:199], v[6:9]
	v_mfma_f32_16x16x32_bf16 v[2:5], v[158:161], v[196:199], v[2:5]
	v_mfma_f32_16x16x32_bf16 v[50:53], v[150:153], v[166:169], v[50:53]
	v_mfma_f32_16x16x32_bf16 v[54:57], v[158:161], v[166:169], v[54:57]
	s_setprio 0
	s_barrier
	s_add_u32 s46, s94, 0x80000
	s_addc_u32 s47, s95, 0
	s_mov_b32 m0, s69
	v_lshl_add_u64 v[212:213], s[46:47], 0, v[0:1]
	global_load_lds_dwordx4 v[212:213], off
	s_mov_b32 m0, s72
	v_lshl_add_u64 v[212:213], s[46:47], 0, v[174:175]
	global_load_lds_dwordx4 v[212:213], off
	s_add_i32 s34, 0, 0x18000
	s_add_i32 s35, 0, 0x1c000
	v_add_u32_e32 v70, s34, v205
	v_add_u32_e32 v158, s35, v205
	ds_read_b128 v[58:61], v70
	ds_read_b128 v[62:65], v70 offset:1024
	ds_read_b128 v[66:69], v70 offset:2048
	ds_read_b128 v[70:73], v70 offset:3072
	ds_read_b128 v[146:149], v158
	ds_read_b128 v[150:153], v158 offset:1024
	ds_read_b128 v[154:157], v158 offset:2048
	ds_read_b128 v[158:161], v158 offset:3072
	ds_read_b128 v[162:165], v207 offset:32768
	ds_read_b128 v[166:169], v207 offset:33792
	ds_read_b128 v[170:173], v207 offset:34816
	ds_read_b128 v[180:183], v207 offset:35840
	ds_read_b128 v[184:187], v207 offset:36864
	ds_read_b128 v[188:191], v207 offset:37888
	ds_read_b128 v[192:195], v207 offset:38912
	ds_read_b128 v[196:199], v207 offset:39936
	s_setprio 1
	s_waitcnt vmcnt(8) lgkmcnt(0)
	s_barrier
	v_mfma_f32_16x16x32_bf16 v[142:145], v[58:61], v[162:165], v[142:145]
	v_mfma_f32_16x16x32_bf16 v[138:141], v[66:69], v[162:165], v[138:141]
	v_mfma_f32_16x16x32_bf16 v[126:129], v[58:61], v[170:173], v[126:129]
	v_mfma_f32_16x16x32_bf16 v[122:125], v[66:69], v[170:173], v[122:125]
	v_mfma_f32_16x16x32_bf16 v[110:113], v[58:61], v[184:187], v[110:113]
	v_mfma_f32_16x16x32_bf16 v[106:109], v[66:69], v[184:187], v[106:109]
	v_mfma_f32_16x16x32_bf16 v[94:97], v[58:61], v[192:195], v[94:97]
	v_mfma_f32_16x16x32_bf16 v[90:93], v[66:69], v[192:195], v[90:93]
	v_mfma_f32_16x16x32_bf16 v[142:145], v[62:65], v[166:169], v[142:145]
	v_mfma_f32_16x16x32_bf16 v[138:141], v[70:73], v[166:169], v[138:141]
	v_mfma_f32_16x16x32_bf16 v[126:129], v[62:65], v[180:183], v[126:129]
	v_mfma_f32_16x16x32_bf16 v[122:125], v[70:73], v[180:183], v[122:125]
	v_mfma_f32_16x16x32_bf16 v[110:113], v[62:65], v[188:191], v[110:113]
	v_mfma_f32_16x16x32_bf16 v[106:109], v[70:73], v[188:191], v[106:109]
	v_mfma_f32_16x16x32_bf16 v[94:97], v[62:65], v[196:199], v[94:97]
	v_mfma_f32_16x16x32_bf16 v[90:93], v[70:73], v[196:199], v[90:93]
	v_mfma_f32_16x16x32_bf16 v[134:137], v[146:149], v[162:165], v[134:137]
	v_mfma_f32_16x16x32_bf16 v[130:133], v[154:157], v[162:165], v[130:133]
	v_mfma_f32_16x16x32_bf16 v[118:121], v[146:149], v[170:173], v[118:121]
	v_mfma_f32_16x16x32_bf16 v[114:117], v[154:157], v[170:173], v[114:117]
	v_mfma_f32_16x16x32_bf16 v[102:105], v[146:149], v[184:187], v[102:105]
	v_mfma_f32_16x16x32_bf16 v[98:101], v[154:157], v[184:187], v[98:101]
	v_mfma_f32_16x16x32_bf16 v[86:89], v[146:149], v[192:195], v[86:89]
	v_mfma_f32_16x16x32_bf16 v[82:85], v[154:157], v[192:195], v[82:85]
	v_mfma_f32_16x16x32_bf16 v[134:137], v[150:153], v[166:169], v[134:137]
	v_mfma_f32_16x16x32_bf16 v[130:133], v[158:161], v[166:169], v[130:133]
	v_mfma_f32_16x16x32_bf16 v[118:121], v[150:153], v[180:183], v[118:121]
	v_mfma_f32_16x16x32_bf16 v[114:117], v[158:161], v[180:183], v[114:117]
	v_mfma_f32_16x16x32_bf16 v[102:105], v[150:153], v[188:191], v[102:105]
	v_mfma_f32_16x16x32_bf16 v[98:101], v[158:161], v[188:191], v[98:101]
	v_mfma_f32_16x16x32_bf16 v[86:89], v[150:153], v[196:199], v[86:89]
	v_mfma_f32_16x16x32_bf16 v[82:85], v[158:161], v[196:199], v[82:85]
	s_setprio 0
	s_barrier
; #define PG8_STAGE(bufoff, gbase, voff) do { _Pragma("unroll") for (int _i = 0; _i < 2; ++_i) \
;         __builtin_amdgcn_global_load_lds((const unsigned*)((const char*)(gbase) + (voff)[_i]), (LAS unsigned*)(lds + (bufoff) + ldsw + _i * 8192), 16, 0, 0); } while (0)
; #define PG8_LDA(dst, b, h) do { _Pragma("unroll") for (int m = 0; m < 4; ++m) _Pragma("unroll") for (int k = 0; k < 2; ++k) dst[m][k] = *(const LAS bf16x8*)(lds + PG8_SA(b, h) + aoff + m * 2048 + k * 1024); } while (0)
; #define PG8_MMA(ai, bj, At, Bt) do { __builtin_amdgcn_s_setprio(1); _Pragma("unroll") for (int m = 0; m < 4; ++m) _Pragma("unroll") for (int n = 0; n < 2; ++n) _Pragma("unroll") for (int k = 0; k < 2; ++k) \
;         acc[ai][bj][m][n] = __builtin_amdgcn_mfma_f32_16x16x32_bf16(Bt[n][k], At[m][k], acc[ai][bj][m][n], 0, 0, 0); __builtin_amdgcn_s_setprio(0); } while (0)
; #define PG8_WAIT_V(n) asm volatile("s_waitcnt vmcnt(" #n ")" ::: "memory")
; #define PG8_WAIT_L(n) asm volatile("s_waitcnt lgkmcnt(" #n ")" ::: "memory")
; #define PG8_BAR __builtin_amdgcn_s_barrier()
; #define PG8_SCHED __builtin_amdgcn_sched_barrier(0)
; template <class Epi, int AMODE>
; __device__ __forceinline__ void gemm_phase(LAS unsigned char* lds, const Gemm g, const StaticOrder& S, const Epi& E, int stagger_us, int tid_in) {
;     ...
;             PG8_LDA(At, 1, 1); PG8_STAGE(PG8_SB(1, 0), b3, voffB); PG8_STAGE(PG8_SB(1, 1), b3 + hstepB, voffB); PG8_STAGE(PG8_SA(1, 0), a3, voffA);
;             PG8_WAIT_V(8); PG8_WAIT_L(0); PG8_BAR; PG8_MMA(1, 0, At, B0); PG8_MMA(1, 1, At, B1); PG8_BAR; PG8_SCHED;
;         }
;         if (wr == 0) PG8_BAR;
	s_add_i32 s34, s34, s13
	s_mov_b32 m0, s34
	v_lshl_add_u64 v[200:201], v[200:201], 0, s[74:75]
	global_load_lds_dwordx4 v[200:201], off
	s_add_i32 m0, s34, 0x2000
	s_add_u32 s6, s6, 0x80080
	v_lshl_add_u64 v[200:201], v[202:203], 0, s[74:75]
	s_addc_u32 s7, s7, 0
	s_add_i32 s34, s35, s13
	global_load_lds_dwordx4 v[200:201], off
	s_mov_b32 m0, s34
	v_lshl_add_u64 v[200:201], s[6:7], 0, v[0:1]
	global_load_lds_dwordx4 v[200:201], off
	s_add_i32 m0, s34, 0x2000
	v_lshl_add_u64 v[200:201], s[6:7], 0, v[174:175]
	global_load_lds_dwordx4 v[200:201], off
	s_mov_b32 m0, s91
	v_lshl_add_u64 v[200:201], v[208:209], 0, s[74:75]
	global_load_lds_dwordx4 v[200:201], off
	s_mov_b32 m0, s96
	v_lshl_add_u64 v[200:201], v[210:211], 0, s[74:75]
	global_load_lds_dwordx4 v[200:201], off
	ds_read_b128 v[162:165], v207 offset:49152
	ds_read_b128 v[166:169], v207 offset:50176
	ds_read_b128 v[170:173], v207 offset:51200
	ds_read_b128 v[180:183], v207 offset:52224
	ds_read_b128 v[184:187], v207 offset:53248
	ds_read_b128 v[188:191], v207 offset:54272
	ds_read_b128 v[192:195], v207 offset:55296
	ds_read_b128 v[196:199], v207 offset:56320
	s_setprio 1
	s_waitcnt vmcnt(8) lgkmcnt(0)
	s_barrier
	v_mfma_f32_16x16x32_bf16 v[78:81], v[58:61], v[162:165], v[78:81]
	v_mfma_f32_16x16x32_bf16 v[74:77], v[66:69], v[162:165], v[74:77]
	v_mfma_f32_16x16x32_bf16 v[46:49], v[58:61], v[170:173], v[46:49]
	v_mfma_f32_16x16x32_bf16 v[42:45], v[66:69], v[170:173], v[42:45]
	v_mfma_f32_16x16x32_bf16 v[30:33], v[58:61], v[184:187], v[30:33]
	v_mfma_f32_16x16x32_bf16 v[26:29], v[66:69], v[184:187], v[26:29]
	v_mfma_f32_16x16x32_bf16 v[14:17], v[58:61], v[192:195], v[14:17]
	v_mfma_f32_16x16x32_bf16 v[10:13], v[66:69], v[192:195], v[10:13]
	v_mfma_f32_16x16x32_bf16 v[78:81], v[62:65], v[166:169], v[78:81]
	v_mfma_f32_16x16x32_bf16 v[74:77], v[70:73], v[166:169], v[74:77]
	v_mfma_f32_16x16x32_bf16 v[46:49], v[62:65], v[180:183], v[46:49]
	v_mfma_f32_16x16x32_bf16 v[42:45], v[70:73], v[180:183], v[42:45]
	v_mfma_f32_16x16x32_bf16 v[30:33], v[62:65], v[188:191], v[30:33]
	v_mfma_f32_16x16x32_bf16 v[26:29], v[70:73], v[188:191], v[26:29]
	v_mfma_f32_16x16x32_bf16 v[14:17], v[62:65], v[196:199], v[14:17]
	v_mfma_f32_16x16x32_bf16 v[10:13], v[70:73], v[196:199], v[10:13]
	v_mfma_f32_16x16x32_bf16 v[50:53], v[146:149], v[162:165], v[50:53]
	v_mfma_f32_16x16x32_bf16 v[70:73], v[150:153], v[166:169], v[50:53]
	v_mfma_f32_16x16x32_bf16 v[50:53], v[154:157], v[162:165], v[54:57]
	v_mfma_f32_16x16x32_bf16 v[38:41], v[146:149], v[170:173], v[38:41]
	v_mfma_f32_16x16x32_bf16 v[34:37], v[154:157], v[170:173], v[34:37]
	v_mfma_f32_16x16x32_bf16 v[22:25], v[146:149], v[184:187], v[22:25]
	v_mfma_f32_16x16x32_bf16 v[18:21], v[154:157], v[184:187], v[18:21]
	v_mfma_f32_16x16x32_bf16 v[6:9], v[146:149], v[192:195], v[6:9]
	v_mfma_f32_16x16x32_bf16 v[2:5], v[154:157], v[192:195], v[2:5]
	v_mfma_f32_16x16x32_bf16 v[66:69], v[158:161], v[166:169], v[50:53]
	v_mfma_f32_16x16x32_bf16 v[38:41], v[150:153], v[180:183], v[38:41]
	v_mfma_f32_16x16x32_bf16 v[34:37], v[158:161], v[180:183], v[34:37]
	v_mfma_f32_16x16x32_bf16 v[22:25], v[150:153], v[188:191], v[22:25]
	v_mfma_f32_16x16x32_bf16 v[18:21], v[158:161], v[188:191], v[18:21]
	v_mfma_f32_16x16x32_bf16 v[6:9], v[150:153], v[196:199], v[6:9]
	v_mfma_f32_16x16x32_bf16 v[2:5], v[158:161], v[196:199], v[2:5]
	s_setprio 0
	s_barrier
	s_add_i32 s31, s31, 2
	s_add_u32 s29, s29, 0x100
	s_addc_u32 s30, s30, 0
	s_cmp_gt_u32 s31, 29
	s_mov_b64 s[46:47], s[4:5]
	s_cbranch_scc0 .LBB0_1199
	s_and_b64 vcc, exec, s[56:57]
	s_cbranch_vccz .LBB0_1202
	s_barrier

; template <class Epi, int AMODE>
; __device__ __forceinline__ void gemm_phase(LAS unsigned char* lds, const Gemm g, const StaticOrder& S, const Epi& E, int stagger_us, int tid_in) {
;     ...
;             PG8_LDB(B0, 0, 0); PG8_LDB(B1, 0, 1); PG8_SCHED; PG8_LDA(At, 0, 0); PG8_STAGE(PG8_SA(1, 1), a1 + hstepA, voffA);
;             PG8_WAIT_V(8); PG8_WAIT_L(0); PG8_BAR; PG8_MMA(0, 0, At, B0); PG8_MMA(0, 1, At, B1); PG8_BAR; PG8_SCHED;
;             PG8_LDA(At, 0, 1); PG8_STAGE(PG8_SB(0, 0), b2, voffB); PG8_STAGE(PG8_SB(0, 1), b2 + hstepB, voffB); PG8_STAGE(PG8_SA(0, 0), a2, voffA);
;             PG8_WAIT_V(8); PG8_WAIT_L(0); PG8_BAR; PG8_MMA(1, 0, At, B0); PG8_MMA(1, 1, At, B1); PG8_BAR; PG8_SCHED;
;             PG8_LDB(B0, 1, 0); PG8_LDB(B1, 1, 1); PG8_SCHED; PG8_LDA(At, 1, 0); PG8_STAGE(PG8_SA(0, 1), a2 + hstepA, voffA);
;             PG8_WAIT_V(8); PG8_WAIT_L(0); PG8_BAR; PG8_MMA(0, 0, At, B0); PG8_MMA(0, 1, At, B1); PG8_BAR; PG8_SCHED;
;             PG8_LDA(At, 1, 1); PG8_STAGE(PG8_SB(1, 0), b3, voffB); PG8_STAGE(PG8_SB(1, 1), b3 + hstepB, voffB); PG8_STAGE(PG8_SA(1, 0), a3, voffA);
;             PG8_WAIT_V(8); PG8_WAIT_L(0); PG8_BAR; PG8_MMA(1, 0, At, B0); PG8_MMA(1, 1, At, B1); PG8_BAR; PG8_SCHED;
;         }
;         if (wr == 0) PG8_BAR;
;         E(acc, cur, wr, wc, fr, fq);
;         if (!has_next) break;
; #pragma unroll
;         for (int a = 0; a < 2; ++a)
; #pragma unroll
;             for (int b = 0; b < 2; ++b)
; #pragma unroll
;                 for (int m = 0; m < 4; ++m)
; #pragma unroll
;                     for (int n = 0; n < 2; ++n) acc[a][b][m][n] = (f32x4){0.f, 0.f, 0.f, 0.f};
;     __device__ __forceinline__ void operator()(f32x4 (&acc)[2][2][4][2], const Unit& u, int wr, int wc, int fr, int fq) const {
;     ...
;             const int tq = tok0 + 8 * fr; const int tA = tq < 0 ? 0 : (tq > TOK - 1 ? TOK - 1 : tq), tB = (tq + 7) > TOK - 1 ? TOK - 1 : (tq + 7);
;             const int bA = batch_of(tA), bB = batch_of(tB); const bool same = __all(bA == bB);
;             const float* bp0 = bias + 256 * u.pn + 32 * wc + 8 * fq;
;             f32x4 bvA[2][2]; float sq[8];
; #pragma unroll
;             for (int am = 0; am < 8; ++am) { int tok = tq + am; tok = tok < 0 ? 0 : (tok > TOK - 1 ? TOK - 1 : tok); sq[am] = LDG(float, ssq + tok); }
; #pragma unroll
;             for (int bj = 0; bj < 2; ++bj)
; #pragma unroll
.LBB0_1298:
	s_ashr_i32 s47, s46, 31
	s_lshl_b64 s[6:7], s[46:47], 20
	s_add_u32 s96, s9, s6
	s_addc_u32 s97, s72, s7
	s_and_b64 s[6:7], s[42:43], exec
	s_cselect_b32 s27, s97, s5
	s_cselect_b32 s28, s96, s4
	s_add_u32 s29, s4, 0x100
	v_mov_b32_e32 v2, 0
	s_addc_u32 s30, s5, 0
	s_mov_b32 s31, -2
	s_mul_i32 s6, s26, 0xfc
	v_add_u32_e32 v222, s6, v197
	v_med3_i32 v240, v222, 0, v238
	v_add_u32_e32 v241, 0xffffe000, v240
	v_lshrrev_b32_e32 v241, 12, v241
	v_add_u32_e32 v241, 4, v241
	v_lshrrev_b32_e32 v242, 11, v240
	v_mov_b32_e32 v243, 0x2000
	v_cmp_gt_i32_e64 s[6:7], v243, v222
	s_nop 1
	v_cndmask_b32_e64 v241, v241, v242, s[6:7]
	s_lshl_b32 s6, s92, 8
	s_ashr_i32 s7, s6, 31
	v_lshl_add_u64 v[236:237], s[6:7], 2, v[184:185]
	v_mad_u64_u32 v[236:237], s[6:7], v241, s15, v[236:237]
	v_med3_i32 v224, v222, 0, v238
	v_lshlrev_b32_e32 v224, 2, v224
	global_load_dword v224, v224, s[56:57]
	v_add_u32_e32 v228, 1, v222
	v_med3_i32 v228, v228, 0, v238
	v_lshlrev_b32_e32 v228, 2, v228
	global_load_dword v228, v228, s[56:57]
	v_add_u32_e32 v231, 2, v222
	v_med3_i32 v231, v231, 0, v238
	v_lshlrev_b32_e32 v231, 2, v231
	global_load_dword v231, v231, s[56:57]
	v_add_u32_e32 v233, 3, v222
	v_med3_i32 v233, v233, 0, v238
	v_lshlrev_b32_e32 v233, 2, v233
	global_load_dword v233, v233, s[56:57]
	v_add_u32_e32 v234, 4, v222
	v_med3_i32 v234, v234, 0, v238
	v_lshlrev_b32_e32 v234, 2, v234
	global_load_dword v234, v234, s[56:57]
	v_add_u32_e32 v239, 5, v222
	v_med3_i32 v239, v239, 0, v238
	v_lshlrev_b32_e32 v239, 2, v239
	global_load_dword v239, v239, s[56:57]
	v_add_u32_e32 v252, 6, v222
	v_med3_i32 v252, v252, 0, v238
	v_lshlrev_b32_e32 v252, 2, v252
	global_load_dword v252, v252, s[56:57]
	v_add_u32_e32 v253, 7, v222
	v_med3_i32 v253, v253, 0, v238
	v_lshlrev_b32_e32 v253, 2, v253
	global_load_dword v253, v253, s[56:57]
	global_load_dwordx4 v[240:243], v[236:237], off
	global_load_dwordx4 v[244:247], v[236:237], off offset:16
	global_load_dwordx4 v[248:251], v[236:237], off offset:512
	global_load_dwordx2 v[222:223], v[236:237], off offset:528
	s_nop 0
	global_load_dwordx2 v[236:237], v[236:237], off offset:536
	v_mov_b32_e32 v3, v2
	v_mov_b32_e32 v4, v2
	v_mov_b32_e32 v5, v2
	v_mov_b32_e32 v14, v2
	v_mov_b32_e32 v15, v2
	v_mov_b32_e32 v16, v2
	v_mov_b32_e32 v17, v2
	v_mov_b32_e32 v10, v2
	v_mov_b32_e32 v11, v2
	v_mov_b32_e32 v12, v2
	v_mov_b32_e32 v13, v2
	v_mov_b32_e32 v26, v2
	v_mov_b32_e32 v27, v2
	v_mov_b32_e32 v28, v2
	v_mov_b32_e32 v29, v2
	v_mov_b32_e32 v6, v2
	v_mov_b32_e32 v7, v2
	v_mov_b32_e32 v8, v2
	v_mov_b32_e32 v9, v2
	v_mov_b32_e32 v42, v2
	v_mov_b32_e32 v43, v2
	v_mov_b32_e32 v44, v2
	v_mov_b32_e32 v45, v2
	v_mov_b32_e32 v30, v2
	v_mov_b32_e32 v31, v2
	v_mov_b32_e32 v32, v2
	v_mov_b32_e32 v33, v2
	v_mov_b32_e32 v58, v2
	v_mov_b32_e32 v59, v2
	v_mov_b32_e32 v60, v2
	v_mov_b32_e32 v61, v2
	v_mov_b32_e32 v74, v2
	v_mov_b32_e32 v75, v2
	v_mov_b32_e32 v76, v2
	v_mov_b32_e32 v77, v2
	v_mov_b32_e32 v22, v2
	v_mov_b32_e32 v23, v2
	v_mov_b32_e32 v24, v2
	v_mov_b32_e32 v25, v2
	v_mov_b32_e32 v34, v2
	v_mov_b32_e32 v35, v2
	v_mov_b32_e32 v36, v2
	v_mov_b32_e32 v37, v2
	v_mov_b32_e32 v18, v2
	v_mov_b32_e32 v19, v2
	v_mov_b32_e32 v20, v2
	v_mov_b32_e32 v21, v2
	v_mov_b32_e32 v50, v2
	v_mov_b32_e32 v51, v2
	v_mov_b32_e32 v52, v2
	v_mov_b32_e32 v53, v2
	v_mov_b32_e32 v38, v2
	v_mov_b32_e32 v39, v2
	v_mov_b32_e32 v40, v2
	v_mov_b32_e32 v41, v2
	v_mov_b32_e32 v46, v2
	v_mov_b32_e32 v47, v2
	v_mov_b32_e32 v48, v2
	v_mov_b32_e32 v49, v2
	v_mov_b32_e32 v54, v2
	v_mov_b32_e32 v55, v2
	v_mov_b32_e32 v56, v2
	v_mov_b32_e32 v57, v2
	v_mov_b32_e32 v66, v2
	v_mov_b32_e32 v67, v2
	v_mov_b32_e32 v68, v2
	v_mov_b32_e32 v69, v2
	v_mov_b32_e32 v78, v2
	v_mov_b32_e32 v79, v2
	v_mov_b32_e32 v80, v2
	v_mov_b32_e32 v81, v2
	v_mov_b32_e32 v62, v2
	v_mov_b32_e32 v63, v2
	v_mov_b32_e32 v64, v2
	v_mov_b32_e32 v65, v2
	v_mov_b32_e32 v70, v2
	v_mov_b32_e32 v71, v2
	v_mov_b32_e32 v72, v2
	v_mov_b32_e32 v73, v2
	v_mov_b32_e32 v86, v2
	v_mov_b32_e32 v87, v2
	v_mov_b32_e32 v88, v2
	v_mov_b32_e32 v89, v2
	v_mov_b32_e32 v94, v2
	v_mov_b32_e32 v95, v2
	v_mov_b32_e32 v96, v2
	v_mov_b32_e32 v97, v2
	v_mov_b32_e32 v98, v2
	v_mov_b32_e32 v99, v2
	v_mov_b32_e32 v100, v2
	v_mov_b32_e32 v101, v2
	v_mov_b32_e32 v106, v2
	v_mov_b32_e32 v107, v2
	v_mov_b32_e32 v108, v2
	v_mov_b32_e32 v109, v2
	v_mov_b32_e32 v82, v2
	v_mov_b32_e32 v83, v2
	v_mov_b32_e32 v84, v2
	v_mov_b32_e32 v85, v2
	v_mov_b32_e32 v90, v2
	v_mov_b32_e32 v91, v2
	v_mov_b32_e32 v92, v2
	v_mov_b32_e32 v93, v2
	v_mov_b32_e32 v102, v2
	v_mov_b32_e32 v103, v2
	v_mov_b32_e32 v104, v2
	v_mov_b32_e32 v105, v2
	v_mov_b32_e32 v110, v2
	v_mov_b32_e32 v111, v2
	v_mov_b32_e32 v112, v2
	v_mov_b32_e32 v113, v2
	v_mov_b32_e32 v114, v2
	v_mov_b32_e32 v115, v2
	v_mov_b32_e32 v116, v2
	v_mov_b32_e32 v117, v2
	v_mov_b32_e32 v118, v2
	v_mov_b32_e32 v119, v2
	v_mov_b32_e32 v120, v2
	v_mov_b32_e32 v121, v2
	v_mov_b32_e32 v122, v2
	v_mov_b32_e32 v123, v2
	v_mov_b32_e32 v124, v2
	v_mov_b32_e32 v125, v2
	v_mov_b32_e32 v126, v2
	v_mov_b32_e32 v127, v2
	v_mov_b32_e32 v128, v2
	v_mov_b32_e32 v129, v2
	s_add_i32 m0, s93, 0xc000
	v_lshl_add_u64 v[194:195], s[44:45], 0, v[186:187]
	global_load_lds_dwordx4 v[194:195], off
	s_add_i32 m0, s93, 0xe000
	v_lshl_add_u64 v[194:195], s[44:45], 0, v[188:189]
	global_load_lds_dwordx4 v[194:195], off
	s_add_u32 s4, s44, 0x100
	s_addc_u32 s5, s45, 0
	s_add_i32 s34, 0, 0x10000
	s_cmp_eq_u32 s31, 28
	s_cselect_b32 s43, s95, s5
	s_cselect_b32 s42, s94, s4
	s_cselect_b32 s7, s27, s30
	s_cselect_b32 s6, s28, s29
	s_add_i32 s35, 0, 0x14000
	v_add_u32_e32 v142, s34, v196
	v_add_u32_e32 v158, s35, v196
	ds_read_b128 v[130:133], v142
	ds_read_b128 v[134:137], v142 offset:1024
	ds_read_b128 v[138:141], v142 offset:2048
	ds_read_b128 v[142:145], v142 offset:3072
	ds_read_b128 v[146:149], v158
	ds_read_b128 v[150:153], v158 offset:1024
	ds_read_b128 v[154:157], v158 offset:2048
	ds_read_b128 v[158:161], v158 offset:3072
	ds_read_b128 v[162:165], v201
	ds_read_b128 v[166:169], v201 offset:1024
	ds_read_b128 v[170:173], v201 offset:2048
	ds_read_b128 v[174:177], v201 offset:3072
	ds_read_b128 v[190:193], v201 offset:4096
	ds_read_b128 v[202:205], v201 offset:5120
	ds_read_b128 v[206:209], v201 offset:6144
	ds_read_b128 v[210:213], v201 offset:7168
	s_setprio 1
	s_waitcnt lgkmcnt(0)
	s_barrier
; #define PG8_STAGE(bufoff, gbase, voff) do { _Pragma("unroll") for (int _i = 0; _i < 2; ++_i) \
;         __builtin_amdgcn_global_load_lds((const unsigned*)((const char*)(gbase) + (voff)[_i]), (LAS unsigned*)(lds + (bufoff) + ldsw + _i * 8192), 16, 0, 0); } while (0)
; #define PG8_LDA(dst, b, h) do { _Pragma("unroll") for (int m = 0; m < 4; ++m) _Pragma("unroll") for (int k = 0; k < 2; ++k) dst[m][k] = *(const LAS bf16x8*)(lds + PG8_SA(b, h) + aoff + m * 2048 + k * 1024); } while (0)
; #define PG8_MMA(ai, bj, At, Bt) do { __builtin_amdgcn_s_setprio(1); _Pragma("unroll") for (int m = 0; m < 4; ++m) _Pragma("unroll") for (int n = 0; n < 2; ++n) _Pragma("unroll") for (int k = 0; k < 2; ++k) \
;         acc[ai][bj][m][n] = __builtin_amdgcn_mfma_f32_16x16x32_bf16(Bt[n][k], At[m][k], acc[ai][bj][m][n], 0, 0, 0); __builtin_amdgcn_s_setprio(0); } while (0)
; #define PG8_WAIT_V(n) asm volatile("s_waitcnt vmcnt(" #n ")" ::: "memory")
; #define PG8_WAIT_L(n) asm volatile("s_waitcnt lgkmcnt(" #n ")" ::: "memory")
; #define PG8_BAR __builtin_amdgcn_s_barrier()
; #define PG8_SCHED __builtin_amdgcn_sched_barrier(0)
; template <class Epi, int AMODE>
; __device__ __forceinline__ void gemm_phase(LAS unsigned char* lds, const Gemm g, const StaticOrder& S, const Epi& E, int stagger_us, int tid_in) {
;     ...
;             PG8_WAIT_V(8); PG8_WAIT_L(0); PG8_BAR; PG8_MMA(0, 0, At, B0); PG8_MMA(0, 1, At, B1); PG8_BAR; PG8_SCHED;
;             PG8_LDA(At, 0, 1); PG8_STAGE(PG8_SB(0, 0), b2, voffB); PG8_STAGE(PG8_SB(0, 1), b2 + hstepB, voffB); PG8_STAGE(PG8_SA(0, 0), a2, voffA);
;             PG8_WAIT_V(8); PG8_WAIT_L(0); PG8_BAR; PG8_MMA(1, 0, At, B0); PG8_MMA(1, 1, At, B1); PG8_BAR; PG8_SCHED;
	v_mfma_f32_16x16x32_bf16 v[126:129], v[130:133], v[162:165], v[126:129]
	v_mfma_f32_16x16x32_bf16 v[122:125], v[138:141], v[162:165], v[122:125]
	v_mfma_f32_16x16x32_bf16 v[118:121], v[130:133], v[170:173], v[118:121]
	v_mfma_f32_16x16x32_bf16 v[114:117], v[138:141], v[170:173], v[114:117]
	v_mfma_f32_16x16x32_bf16 v[110:113], v[130:133], v[190:193], v[110:113]
	v_mfma_f32_16x16x32_bf16 v[102:105], v[138:141], v[190:193], v[102:105]
	v_mfma_f32_16x16x32_bf16 v[90:93], v[130:133], v[206:209], v[90:93]
	v_mfma_f32_16x16x32_bf16 v[82:85], v[138:141], v[206:209], v[82:85]
	v_mfma_f32_16x16x32_bf16 v[126:129], v[134:137], v[166:169], v[126:129]
	v_mfma_f32_16x16x32_bf16 v[122:125], v[142:145], v[166:169], v[122:125]
	v_mfma_f32_16x16x32_bf16 v[118:121], v[134:137], v[174:177], v[118:121]
	v_mfma_f32_16x16x32_bf16 v[114:117], v[142:145], v[174:177], v[114:117]
	v_mfma_f32_16x16x32_bf16 v[110:113], v[134:137], v[202:205], v[110:113]
	v_mfma_f32_16x16x32_bf16 v[102:105], v[142:145], v[202:205], v[102:105]
	v_mfma_f32_16x16x32_bf16 v[90:93], v[134:137], v[210:213], v[90:93]
	v_mfma_f32_16x16x32_bf16 v[82:85], v[142:145], v[210:213], v[82:85]
	v_mfma_f32_16x16x32_bf16 v[106:109], v[146:149], v[162:165], v[106:109]
	v_mfma_f32_16x16x32_bf16 v[98:101], v[154:157], v[162:165], v[98:101]
	v_mfma_f32_16x16x32_bf16 v[94:97], v[146:149], v[170:173], v[94:97]
	v_mfma_f32_16x16x32_bf16 v[86:89], v[154:157], v[170:173], v[86:89]
	v_mfma_f32_16x16x32_bf16 v[70:73], v[146:149], v[190:193], v[70:73]
	v_mfma_f32_16x16x32_bf16 v[62:65], v[154:157], v[190:193], v[62:65]
	v_mfma_f32_16x16x32_bf16 v[78:81], v[146:149], v[206:209], v[78:81]
	v_mfma_f32_16x16x32_bf16 v[66:69], v[154:157], v[206:209], v[66:69]
	v_mfma_f32_16x16x32_bf16 v[106:109], v[150:153], v[166:169], v[106:109]
	v_mfma_f32_16x16x32_bf16 v[98:101], v[158:161], v[166:169], v[98:101]
	v_mfma_f32_16x16x32_bf16 v[94:97], v[150:153], v[174:177], v[94:97]
	v_mfma_f32_16x16x32_bf16 v[86:89], v[158:161], v[174:177], v[86:89]
	v_mfma_f32_16x16x32_bf16 v[70:73], v[150:153], v[202:205], v[70:73]
	v_mfma_f32_16x16x32_bf16 v[62:65], v[158:161], v[202:205], v[62:65]
	v_mfma_f32_16x16x32_bf16 v[78:81], v[150:153], v[210:213], v[78:81]
	v_mfma_f32_16x16x32_bf16 v[66:69], v[158:161], v[210:213], v[66:69]
	s_setprio 0
	s_barrier
	s_add_i32 s34, s34, s91
	s_mov_b32 m0, s34
	v_lshl_add_u64 v[194:195], s[6:7], 0, v[0:1]
	global_load_lds_dwordx4 v[194:195], off
	s_add_i32 m0, s34, 0x2000
	s_add_u32 s44, s6, 0x80000
	v_lshl_add_u64 v[214:215], s[6:7], 0, v[182:183]
	s_addc_u32 s45, s7, 0
	s_add_i32 s34, s35, s91
	global_load_lds_dwordx4 v[214:215], off
	v_lshl_add_u64 v[216:217], s[44:45], 0, v[0:1]
	s_mov_b32 m0, s34
	v_lshl_add_u64 v[218:219], s[42:43], 0, v[180:181]
	global_load_lds_dwordx4 v[216:217], off
	s_add_i32 m0, s34, 0x2000
	v_lshl_add_u64 v[216:217], s[44:45], 0, v[182:183]
	global_load_lds_dwordx4 v[216:217], off
	s_mov_b32 m0, s93
	v_lshl_add_u64 v[216:217], s[42:43], 0, v[178:179]
	global_load_lds_dwordx4 v[216:217], off
	s_mov_b32 m0, s83
	s_nop 0
	global_load_lds_dwordx4 v[218:219], off
	ds_read_b128 v[162:165], v201 offset:16384
	ds_read_b128 v[166:169], v201 offset:17408
	ds_read_b128 v[170:173], v201 offset:18432
	ds_read_b128 v[174:177], v201 offset:19456
	ds_read_b128 v[190:193], v201 offset:20480
	ds_read_b128 v[202:205], v201 offset:21504
	ds_read_b128 v[206:209], v201 offset:22528
	ds_read_b128 v[210:213], v201 offset:23552
	s_setprio 1
	s_waitcnt lgkmcnt(0)
	s_barrier
	v_mfma_f32_16x16x32_bf16 v[54:57], v[130:133], v[162:165], v[54:57]
	v_mfma_f32_16x16x32_bf16 v[46:49], v[138:141], v[162:165], v[46:49]
	v_mfma_f32_16x16x32_bf16 v[38:41], v[130:133], v[170:173], v[38:41]
	v_mfma_f32_16x16x32_bf16 v[50:53], v[138:141], v[170:173], v[50:53]
	v_mfma_f32_16x16x32_bf16 v[18:21], v[130:133], v[190:193], v[18:21]
	v_mfma_f32_16x16x32_bf16 v[34:37], v[138:141], v[190:193], v[34:37]
	v_mfma_f32_16x16x32_bf16 v[22:25], v[130:133], v[206:209], v[22:25]
	v_mfma_f32_16x16x32_bf16 v[74:77], v[138:141], v[206:209], v[74:77]
	v_mfma_f32_16x16x32_bf16 v[54:57], v[134:137], v[166:169], v[54:57]
	v_mfma_f32_16x16x32_bf16 v[46:49], v[142:145], v[166:169], v[46:49]
	v_mfma_f32_16x16x32_bf16 v[38:41], v[134:137], v[174:177], v[38:41]
	v_mfma_f32_16x16x32_bf16 v[50:53], v[142:145], v[174:177], v[50:53]
	v_mfma_f32_16x16x32_bf16 v[18:21], v[134:137], v[202:205], v[18:21]
	v_mfma_f32_16x16x32_bf16 v[34:37], v[142:145], v[202:205], v[34:37]
	v_mfma_f32_16x16x32_bf16 v[22:25], v[134:137], v[210:213], v[22:25]
	v_mfma_f32_16x16x32_bf16 v[74:77], v[142:145], v[210:213], v[74:77]
	v_mfma_f32_16x16x32_bf16 v[58:61], v[146:149], v[162:165], v[58:61]
	v_mfma_f32_16x16x32_bf16 v[30:33], v[154:157], v[162:165], v[30:33]
	v_mfma_f32_16x16x32_bf16 v[42:45], v[146:149], v[170:173], v[42:45]
	v_mfma_f32_16x16x32_bf16 v[6:9], v[154:157], v[170:173], v[6:9]
	v_mfma_f32_16x16x32_bf16 v[26:29], v[146:149], v[190:193], v[26:29]
	v_mfma_f32_16x16x32_bf16 v[10:13], v[154:157], v[190:193], v[10:13]
	v_mfma_f32_16x16x32_bf16 v[14:17], v[146:149], v[206:209], v[14:17]
	v_mfma_f32_16x16x32_bf16 v[2:5], v[154:157], v[206:209], v[2:5]
	v_mfma_f32_16x16x32_bf16 v[58:61], v[150:153], v[166:169], v[58:61]
	v_mfma_f32_16x16x32_bf16 v[30:33], v[158:161], v[166:169], v[30:33]
	v_mfma_f32_16x16x32_bf16 v[42:45], v[150:153], v[174:177], v[42:45]
	v_mfma_f32_16x16x32_bf16 v[6:9], v[158:161], v[174:177], v[6:9]
	v_mfma_f32_16x16x32_bf16 v[26:29], v[150:153], v[202:205], v[26:29]
	v_mfma_f32_16x16x32_bf16 v[10:13], v[158:161], v[202:205], v[10:13]
	v_mfma_f32_16x16x32_bf16 v[14:17], v[150:153], v[210:213], v[14:17]
	v_mfma_f32_16x16x32_bf16 v[2:5], v[158:161], v[210:213], v[2:5]
	s_setprio 0
	s_barrier
; #define PG8_STAGE(bufoff, gbase, voff) do { _Pragma("unroll") for (int _i = 0; _i < 2; ++_i) \
;         __builtin_amdgcn_global_load_lds((const unsigned*)((const char*)(gbase) + (voff)[_i]), (LAS unsigned*)(lds + (bufoff) + ldsw + _i * 8192), 16, 0, 0); } while (0)
; #define PG8_LDA(dst, b, h) do { _Pragma("unroll") for (int m = 0; m < 4; ++m) _Pragma("unroll") for (int k = 0; k < 2; ++k) dst[m][k] = *(const LAS bf16x8*)(lds + PG8_SA(b, h) + aoff + m * 2048 + k * 1024); } while (0)
; #define PG8_LDB(dst, b, h) do { _Pragma("unroll") for (int n = 0; n < 2; ++n) _Pragma("unroll") for (int k = 0; k < 2; ++k) dst[n][k] = *(const LAS bf16x8*)(lds + PG8_SB(b, h) + boff + n * 2048 + k * 1024); } while (0)
; #define PG8_MMA(ai, bj, At, Bt) do { __builtin_amdgcn_s_setprio(1); _Pragma("unroll") for (int m = 0; m < 4; ++m) _Pragma("unroll") for (int n = 0; n < 2; ++n) _Pragma("unroll") for (int k = 0; k < 2; ++k) \
;         acc[ai][bj][m][n] = __builtin_amdgcn_mfma_f32_16x16x32_bf16(Bt[n][k], At[m][k], acc[ai][bj][m][n], 0, 0, 0); __builtin_amdgcn_s_setprio(0); } while (0)
; #define PG8_WAIT_V(n) asm volatile("s_waitcnt vmcnt(" #n ")" ::: "memory")
; #define PG8_WAIT_L(n) asm volatile("s_waitcnt lgkmcnt(" #n ")" ::: "memory")
; #define PG8_BAR __builtin_amdgcn_s_barrier()
; #define PG8_SCHED __builtin_amdgcn_sched_barrier(0)
; template <class Epi, int AMODE>
; __device__ __forceinline__ void gemm_phase(LAS unsigned char* lds, const Gemm g, const StaticOrder& S, const Epi& E, int stagger_us, int tid_in) {
;     ...
;             PG8_LDB(B0, 1, 0); PG8_LDB(B1, 1, 1); PG8_SCHED; PG8_LDA(At, 1, 0); PG8_STAGE(PG8_SA(0, 1), a2 + hstepA, voffA);
;             PG8_WAIT_V(8); PG8_WAIT_L(0); PG8_BAR; PG8_MMA(0, 0, At, B0); PG8_MMA(0, 1, At, B1); PG8_BAR; PG8_SCHED;
;             PG8_LDA(At, 1, 1); PG8_STAGE(PG8_SB(1, 0), b3, voffB); PG8_STAGE(PG8_SB(1, 1), b3 + hstepB, voffB); PG8_STAGE(PG8_SA(1, 0), a3, voffA);
;             PG8_WAIT_V(8); PG8_WAIT_L(0); PG8_BAR; PG8_MMA(1, 0, At, B0); PG8_MMA(1, 1, At, B1); PG8_BAR; PG8_SCHED;
	s_add_u32 s42, s42, 0x4000
	s_addc_u32 s43, s43, 0
	s_mov_b32 m0, s79
	v_lshl_add_u64 v[220:221], s[42:43], 0, v[178:179]
	global_load_lds_dwordx4 v[220:221], off
	s_mov_b32 m0, s87
	v_lshl_add_u64 v[220:221], s[42:43], 0, v[180:181]
	global_load_lds_dwordx4 v[220:221], off
	s_add_i32 s34, 0, 0x18000
	s_add_i32 s35, 0, 0x1c000
	v_add_u32_e32 v142, s34, v196
	v_add_u32_e32 v158, s35, v196
	ds_read_b128 v[130:133], v142
	ds_read_b128 v[134:137], v142 offset:1024
	ds_read_b128 v[138:141], v142 offset:2048
	ds_read_b128 v[142:145], v142 offset:3072
	ds_read_b128 v[146:149], v158
	ds_read_b128 v[150:153], v158 offset:1024
	ds_read_b128 v[154:157], v158 offset:2048
	ds_read_b128 v[158:161], v158 offset:3072
	ds_read_b128 v[162:165], v201 offset:32768
	ds_read_b128 v[166:169], v201 offset:33792
	ds_read_b128 v[170:173], v201 offset:34816
	ds_read_b128 v[174:177], v201 offset:35840
	ds_read_b128 v[190:193], v201 offset:36864
	ds_read_b128 v[202:205], v201 offset:37888
	ds_read_b128 v[206:209], v201 offset:38912
	ds_read_b128 v[210:213], v201 offset:39936
	s_setprio 1
	s_waitcnt vmcnt(8) lgkmcnt(0)
	s_barrier
	v_mfma_f32_16x16x32_bf16 v[126:129], v[130:133], v[162:165], v[126:129]
	v_mfma_f32_16x16x32_bf16 v[122:125], v[138:141], v[162:165], v[122:125]
	v_mfma_f32_16x16x32_bf16 v[118:121], v[130:133], v[170:173], v[118:121]
	v_mfma_f32_16x16x32_bf16 v[114:117], v[138:141], v[170:173], v[114:117]
	v_mfma_f32_16x16x32_bf16 v[110:113], v[130:133], v[190:193], v[110:113]
	v_mfma_f32_16x16x32_bf16 v[102:105], v[138:141], v[190:193], v[102:105]
	v_mfma_f32_16x16x32_bf16 v[90:93], v[130:133], v[206:209], v[90:93]
	v_mfma_f32_16x16x32_bf16 v[82:85], v[138:141], v[206:209], v[82:85]
	v_mfma_f32_16x16x32_bf16 v[126:129], v[134:137], v[166:169], v[126:129]
	v_mfma_f32_16x16x32_bf16 v[122:125], v[142:145], v[166:169], v[122:125]
	v_mfma_f32_16x16x32_bf16 v[118:121], v[134:137], v[174:177], v[118:121]
	v_mfma_f32_16x16x32_bf16 v[114:117], v[142:145], v[174:177], v[114:117]
	v_mfma_f32_16x16x32_bf16 v[110:113], v[134:137], v[202:205], v[110:113]
	v_mfma_f32_16x16x32_bf16 v[102:105], v[142:145], v[202:205], v[102:105]
	v_mfma_f32_16x16x32_bf16 v[90:93], v[134:137], v[210:213], v[90:93]
	v_mfma_f32_16x16x32_bf16 v[82:85], v[142:145], v[210:213], v[82:85]
	v_mfma_f32_16x16x32_bf16 v[106:109], v[146:149], v[162:165], v[106:109]
	v_mfma_f32_16x16x32_bf16 v[98:101], v[154:157], v[162:165], v[98:101]
	v_mfma_f32_16x16x32_bf16 v[94:97], v[146:149], v[170:173], v[94:97]
	v_mfma_f32_16x16x32_bf16 v[86:89], v[154:157], v[170:173], v[86:89]
	v_mfma_f32_16x16x32_bf16 v[70:73], v[146:149], v[190:193], v[70:73]
	v_mfma_f32_16x16x32_bf16 v[62:65], v[154:157], v[190:193], v[62:65]
	v_mfma_f32_16x16x32_bf16 v[78:81], v[146:149], v[206:209], v[78:81]
	v_mfma_f32_16x16x32_bf16 v[66:69], v[154:157], v[206:209], v[66:69]
	v_mfma_f32_16x16x32_bf16 v[106:109], v[150:153], v[166:169], v[106:109]
	v_mfma_f32_16x16x32_bf16 v[98:101], v[158:161], v[166:169], v[98:101]
	v_mfma_f32_16x16x32_bf16 v[94:97], v[150:153], v[174:177], v[94:97]
	v_mfma_f32_16x16x32_bf16 v[86:89], v[158:161], v[174:177], v[86:89]
	v_mfma_f32_16x16x32_bf16 v[70:73], v[150:153], v[202:205], v[70:73]
	v_mfma_f32_16x16x32_bf16 v[62:65], v[158:161], v[202:205], v[62:65]
	v_mfma_f32_16x16x32_bf16 v[78:81], v[150:153], v[210:213], v[78:81]
	v_mfma_f32_16x16x32_bf16 v[66:69], v[158:161], v[210:213], v[66:69]
	s_setprio 0
	s_barrier
	s_add_i32 s34, s34, s91
	s_mov_b32 m0, s34
	v_lshl_add_u64 v[194:195], v[194:195], 0, s[74:75]
	global_load_lds_dwordx4 v[194:195], off
	s_add_i32 m0, s34, 0x2000
	s_add_u32 s6, s6, 0x80080
	v_lshl_add_u64 v[194:195], v[214:215], 0, s[74:75]
	s_addc_u32 s7, s7, 0
	s_add_i32 s34, s35, s91
	global_load_lds_dwordx4 v[194:195], off
	s_mov_b32 m0, s34
	v_lshl_add_u64 v[194:195], s[6:7], 0, v[0:1]
	global_load_lds_dwordx4 v[194:195], off
	s_add_i32 m0, s34, 0x2000
	v_lshl_add_u64 v[194:195], s[6:7], 0, v[182:183]
	global_load_lds_dwordx4 v[194:195], off
	s_mov_b32 m0, s67
	v_lshl_add_u64 v[194:195], v[216:217], 0, s[74:75]
	global_load_lds_dwordx4 v[194:195], off
	s_mov_b32 m0, s85
	v_lshl_add_u64 v[194:195], v[218:219], 0, s[74:75]
	global_load_lds_dwordx4 v[194:195], off
	ds_read_b128 v[162:165], v201 offset:49152
	ds_read_b128 v[166:169], v201 offset:50176
	ds_read_b128 v[170:173], v201 offset:51200
	ds_read_b128 v[174:177], v201 offset:52224
	ds_read_b128 v[190:193], v201 offset:53248
	ds_read_b128 v[202:205], v201 offset:54272
	ds_read_b128 v[206:209], v201 offset:55296
	ds_read_b128 v[210:213], v201 offset:56320
	s_setprio 1
	s_waitcnt vmcnt(8) lgkmcnt(0)
	s_barrier
	v_mfma_f32_16x16x32_bf16 v[54:57], v[130:133], v[162:165], v[54:57]
	v_mfma_f32_16x16x32_bf16 v[46:49], v[138:141], v[162:165], v[46:49]
	v_mfma_f32_16x16x32_bf16 v[38:41], v[130:133], v[170:173], v[38:41]
	v_mfma_f32_16x16x32_bf16 v[50:53], v[138:141], v[170:173], v[50:53]
	v_mfma_f32_16x16x32_bf16 v[18:21], v[130:133], v[190:193], v[18:21]
	v_mfma_f32_16x16x32_bf16 v[34:37], v[138:141], v[190:193], v[34:37]
	v_mfma_f32_16x16x32_bf16 v[22:25], v[130:133], v[206:209], v[22:25]
	v_mfma_f32_16x16x32_bf16 v[74:77], v[138:141], v[206:209], v[74:77]
	v_mfma_f32_16x16x32_bf16 v[54:57], v[134:137], v[166:169], v[54:57]
	v_mfma_f32_16x16x32_bf16 v[46:49], v[142:145], v[166:169], v[46:49]
	v_mfma_f32_16x16x32_bf16 v[38:41], v[134:137], v[174:177], v[38:41]
	v_mfma_f32_16x16x32_bf16 v[50:53], v[142:145], v[174:177], v[50:53]
	v_mfma_f32_16x16x32_bf16 v[18:21], v[134:137], v[202:205], v[18:21]
	v_mfma_f32_16x16x32_bf16 v[34:37], v[142:145], v[202:205], v[34:37]
	v_mfma_f32_16x16x32_bf16 v[22:25], v[134:137], v[210:213], v[22:25]
	v_mfma_f32_16x16x32_bf16 v[74:77], v[142:145], v[210:213], v[74:77]
	v_mfma_f32_16x16x32_bf16 v[58:61], v[146:149], v[162:165], v[58:61]
	v_mfma_f32_16x16x32_bf16 v[30:33], v[154:157], v[162:165], v[30:33]
	v_mfma_f32_16x16x32_bf16 v[42:45], v[146:149], v[170:173], v[42:45]
	v_mfma_f32_16x16x32_bf16 v[6:9], v[154:157], v[170:173], v[6:9]
	v_mfma_f32_16x16x32_bf16 v[26:29], v[146:149], v[190:193], v[26:29]
	v_mfma_f32_16x16x32_bf16 v[10:13], v[154:157], v[190:193], v[10:13]
	v_mfma_f32_16x16x32_bf16 v[14:17], v[146:149], v[206:209], v[14:17]
	v_mfma_f32_16x16x32_bf16 v[2:5], v[154:157], v[206:209], v[2:5]
	v_mfma_f32_16x16x32_bf16 v[58:61], v[150:153], v[166:169], v[58:61]
	v_mfma_f32_16x16x32_bf16 v[30:33], v[158:161], v[166:169], v[30:33]
	v_mfma_f32_16x16x32_bf16 v[42:45], v[150:153], v[174:177], v[42:45]
	v_mfma_f32_16x16x32_bf16 v[6:9], v[158:161], v[174:177], v[6:9]
	v_mfma_f32_16x16x32_bf16 v[26:29], v[150:153], v[202:205], v[26:29]
	v_mfma_f32_16x16x32_bf16 v[10:13], v[158:161], v[202:205], v[10:13]
	v_mfma_f32_16x16x32_bf16 v[14:17], v[150:153], v[210:213], v[14:17]
	v_mfma_f32_16x16x32_bf16 v[2:5], v[158:161], v[210:213], v[2:5]
	s_setprio 0
	s_barrier
	s_add_i32 s31, s31, 2
	s_add_u32 s29, s29, 0x100
	s_addc_u32 s30, s30, 0
	s_cmp_gt_u32 s31, 29
	s_mov_b64 s[44:45], s[4:5]
; #define PG8_STAGE(bufoff, gbase, voff) do { _Pragma("unroll") for (int _i = 0; _i < 2; ++_i) \
;         __builtin_amdgcn_global_load_lds((const unsigned*)((const char*)(gbase) + (voff)[_i]), (LAS unsigned*)(lds + (bufoff) + ldsw + _i * 8192), 16, 0, 0); } while (0)
; #define PG8_LDA(dst, b, h) do { _Pragma("unroll") for (int m = 0; m < 4; ++m) _Pragma("unroll") for (int k = 0; k < 2; ++k) dst[m][k] = *(const LAS bf16x8*)(lds + PG8_SA(b, h) + aoff + m * 2048 + k * 1024); } while (0)
; #define PG8_LDB(dst, b, h) do { _Pragma("unroll") for (int n = 0; n < 2; ++n) _Pragma("unroll") for (int k = 0; k < 2; ++k) dst[n][k] = *(const LAS bf16x8*)(lds + PG8_SB(b, h) + boff + n * 2048 + k * 1024); } while (0)
; #define PG8_MMA(ai, bj, At, Bt) do { __builtin_amdgcn_s_setprio(1); _Pragma("unroll") for (int m = 0; m < 4; ++m) _Pragma("unroll") for (int n = 0; n < 2; ++n) _Pragma("unroll") for (int k = 0; k < 2; ++k) \
;         acc[ai][bj][m][n] = __builtin_amdgcn_mfma_f32_16x16x32_bf16(Bt[n][k], At[m][k], acc[ai][bj][m][n], 0, 0, 0); __builtin_amdgcn_s_setprio(0); } while (0)
; #define PG8_WAIT_V(n) asm volatile("s_waitcnt vmcnt(" #n ")" ::: "memory")
; #define PG8_WAIT_L(n) asm volatile("s_waitcnt lgkmcnt(" #n ")" ::: "memory")
; #define PG8_BAR __builtin_amdgcn_s_barrier()
; #define PG8_SCHED __builtin_amdgcn_sched_barrier(0)
; template <class Epi, int AMODE>
; __device__ __forceinline__ void gemm_phase(LAS unsigned char* lds, const Gemm g, const StaticOrder& S, const Epi& E, int stagger_us, int tid_in) {
;     ...
;             PG8_LDB(B0, 0, 0); PG8_LDB(B1, 0, 1); PG8_SCHED; PG8_LDA(At, 0, 0); PG8_STAGE(PG8_SA(1, 1), a1 + hstepA, voffA);
;             PG8_WAIT_V(8); PG8_WAIT_L(0); PG8_BAR; PG8_MMA(0, 0, At, B0); PG8_MMA(0, 1, At, B1); PG8_BAR; PG8_SCHED;
;             PG8_LDA(At, 0, 1); PG8_STAGE(PG8_SB(0, 0), b2, voffB); PG8_STAGE(PG8_SB(0, 1), b2 + hstepB, voffB); PG8_STAGE(PG8_SA(0, 0), a2, voffA);
;             PG8_WAIT_V(8); PG8_WAIT_L(0); PG8_BAR; PG8_MMA(1, 0, At, B0); PG8_MMA(1, 1, At, B1); PG8_BAR; PG8_SCHED;
.LBB0_1299:
	s_add_i32 m0, s93, 0xc000
	v_lshl_add_u64 v[194:195], s[44:45], 0, v[186:187]
	global_load_lds_dwordx4 v[194:195], off
	s_add_i32 m0, s93, 0xe000
	v_lshl_add_u64 v[194:195], s[44:45], 0, v[188:189]
	global_load_lds_dwordx4 v[194:195], off
	s_add_u32 s4, s44, 0x100
	s_addc_u32 s5, s45, 0
	s_add_i32 s34, 0, 0x10000
	s_cmp_eq_u32 s31, 28
	s_cselect_b32 s43, s95, s5
	s_cselect_b32 s42, s94, s4
	s_cselect_b32 s7, s27, s30
	s_cselect_b32 s6, s28, s29
	s_add_i32 s35, 0, 0x14000
	v_add_u32_e32 v142, s34, v196
	v_add_u32_e32 v158, s35, v196
	ds_read_b128 v[130:133], v142
	ds_read_b128 v[134:137], v142 offset:1024
	ds_read_b128 v[138:141], v142 offset:2048
	ds_read_b128 v[142:145], v142 offset:3072
	ds_read_b128 v[146:149], v158
	ds_read_b128 v[150:153], v158 offset:1024
	ds_read_b128 v[154:157], v158 offset:2048
	ds_read_b128 v[158:161], v158 offset:3072
	ds_read_b128 v[162:165], v201
	ds_read_b128 v[166:169], v201 offset:1024
	ds_read_b128 v[170:173], v201 offset:2048
	ds_read_b128 v[174:177], v201 offset:3072
	ds_read_b128 v[190:193], v201 offset:4096
	ds_read_b128 v[202:205], v201 offset:5120
	ds_read_b128 v[206:209], v201 offset:6144
	ds_read_b128 v[210:213], v201 offset:7168
	s_setprio 1
	s_waitcnt vmcnt(8) lgkmcnt(0)
	s_barrier
	v_mfma_f32_16x16x32_bf16 v[126:129], v[130:133], v[162:165], v[126:129]
	v_mfma_f32_16x16x32_bf16 v[122:125], v[138:141], v[162:165], v[122:125]
	v_mfma_f32_16x16x32_bf16 v[118:121], v[130:133], v[170:173], v[118:121]
	v_mfma_f32_16x16x32_bf16 v[114:117], v[138:141], v[170:173], v[114:117]
	v_mfma_f32_16x16x32_bf16 v[110:113], v[130:133], v[190:193], v[110:113]
	v_mfma_f32_16x16x32_bf16 v[102:105], v[138:141], v[190:193], v[102:105]
	v_mfma_f32_16x16x32_bf16 v[90:93], v[130:133], v[206:209], v[90:93]
	v_mfma_f32_16x16x32_bf16 v[82:85], v[138:141], v[206:209], v[82:85]
	v_mfma_f32_16x16x32_bf16 v[126:129], v[134:137], v[166:169], v[126:129]
	v_mfma_f32_16x16x32_bf16 v[122:125], v[142:145], v[166:169], v[122:125]
	v_mfma_f32_16x16x32_bf16 v[118:121], v[134:137], v[174:177], v[118:121]
	v_mfma_f32_16x16x32_bf16 v[114:117], v[142:145], v[174:177], v[114:117]
	v_mfma_f32_16x16x32_bf16 v[110:113], v[134:137], v[202:205], v[110:113]
	v_mfma_f32_16x16x32_bf16 v[102:105], v[142:145], v[202:205], v[102:105]
	v_mfma_f32_16x16x32_bf16 v[90:93], v[134:137], v[210:213], v[90:93]
	v_mfma_f32_16x16x32_bf16 v[82:85], v[142:145], v[210:213], v[82:85]
	v_mfma_f32_16x16x32_bf16 v[106:109], v[146:149], v[162:165], v[106:109]
	v_mfma_f32_16x16x32_bf16 v[98:101], v[154:157], v[162:165], v[98:101]
	v_mfma_f32_16x16x32_bf16 v[94:97], v[146:149], v[170:173], v[94:97]
	v_mfma_f32_16x16x32_bf16 v[86:89], v[154:157], v[170:173], v[86:89]
	v_mfma_f32_16x16x32_bf16 v[70:73], v[146:149], v[190:193], v[70:73]
	v_mfma_f32_16x16x32_bf16 v[62:65], v[154:157], v[190:193], v[62:65]
	v_mfma_f32_16x16x32_bf16 v[78:81], v[146:149], v[206:209], v[78:81]
	v_mfma_f32_16x16x32_bf16 v[66:69], v[154:157], v[206:209], v[66:69]
	v_mfma_f32_16x16x32_bf16 v[106:109], v[150:153], v[166:169], v[106:109]
	v_mfma_f32_16x16x32_bf16 v[98:101], v[158:161], v[166:169], v[98:101]
	v_mfma_f32_16x16x32_bf16 v[94:97], v[150:153], v[174:177], v[94:97]
	v_mfma_f32_16x16x32_bf16 v[86:89], v[158:161], v[174:177], v[86:89]
	v_mfma_f32_16x16x32_bf16 v[70:73], v[150:153], v[202:205], v[70:73]
	v_mfma_f32_16x16x32_bf16 v[62:65], v[158:161], v[202:205], v[62:65]
	v_mfma_f32_16x16x32_bf16 v[78:81], v[150:153], v[210:213], v[78:81]
	v_mfma_f32_16x16x32_bf16 v[66:69], v[158:161], v[210:213], v[66:69]
	s_setprio 0
	s_barrier
	s_add_i32 s34, s34, s91
	s_mov_b32 m0, s34
	v_lshl_add_u64 v[194:195], s[6:7], 0, v[0:1]
	global_load_lds_dwordx4 v[194:195], off
	s_add_i32 m0, s34, 0x2000
	s_add_u32 s44, s6, 0x80000
	v_lshl_add_u64 v[214:215], s[6:7], 0, v[182:183]
	s_addc_u32 s45, s7, 0
	s_add_i32 s34, s35, s91
	global_load_lds_dwordx4 v[214:215], off
	v_lshl_add_u64 v[216:217], s[44:45], 0, v[0:1]
	s_mov_b32 m0, s34
	v_lshl_add_u64 v[218:219], s[42:43], 0, v[180:181]
	global_load_lds_dwordx4 v[216:217], off
	s_add_i32 m0, s34, 0x2000
	v_lshl_add_u64 v[216:217], s[44:45], 0, v[182:183]
	global_load_lds_dwordx4 v[216:217], off
	s_mov_b32 m0, s93
	v_lshl_add_u64 v[216:217], s[42:43], 0, v[178:179]
	global_load_lds_dwordx4 v[216:217], off
	s_mov_b32 m0, s83
	s_nop 0
	global_load_lds_dwordx4 v[218:219], off
	ds_read_b128 v[162:165], v201 offset:16384
	ds_read_b128 v[166:169], v201 offset:17408
	ds_read_b128 v[170:173], v201 offset:18432
	ds_read_b128 v[174:177], v201 offset:19456
	ds_read_b128 v[190:193], v201 offset:20480
	ds_read_b128 v[202:205], v201 offset:21504
	ds_read_b128 v[206:209], v201 offset:22528
	ds_read_b128 v[210:213], v201 offset:23552
	s_setprio 1
	s_waitcnt vmcnt(8) lgkmcnt(0)
	s_barrier
; #define PG8_STAGE(bufoff, gbase, voff) do { _Pragma("unroll") for (int _i = 0; _i < 2; ++_i) \
;         __builtin_amdgcn_global_load_lds((const unsigned*)((const char*)(gbase) + (voff)[_i]), (LAS unsigned*)(lds + (bufoff) + ldsw + _i * 8192), 16, 0, 0); } while (0)
; #define PG8_LDA(dst, b, h) do { _Pragma("unroll") for (int m = 0; m < 4; ++m) _Pragma("unroll") for (int k = 0; k < 2; ++k) dst[m][k] = *(const LAS bf16x8*)(lds + PG8_SA(b, h) + aoff + m * 2048 + k * 1024); } while (0)
; #define PG8_LDB(dst, b, h) do { _Pragma("unroll") for (int n = 0; n < 2; ++n) _Pragma("unroll") for (int k = 0; k < 2; ++k) dst[n][k] = *(const LAS bf16x8*)(lds + PG8_SB(b, h) + boff + n * 2048 + k * 1024); } while (0)
; #define PG8_MMA(ai, bj, At, Bt) do { __builtin_amdgcn_s_setprio(1); _Pragma("unroll") for (int m = 0; m < 4; ++m) _Pragma("unroll") for (int n = 0; n < 2; ++n) _Pragma("unroll") for (int k = 0; k < 2; ++k) \
;         acc[ai][bj][m][n] = __builtin_amdgcn_mfma_f32_16x16x32_bf16(Bt[n][k], At[m][k], acc[ai][bj][m][n], 0, 0, 0); __builtin_amdgcn_s_setprio(0); } while (0)
; #define PG8_WAIT_V(n) asm volatile("s_waitcnt vmcnt(" #n ")" ::: "memory")
; template <class Epi, int AMODE>
; __device__ __forceinline__ void gemm_phase(LAS unsigned char* lds, const Gemm g, const StaticOrder& S, const Epi& E, int stagger_us, int tid_in) {
;     ...
;             PG8_LDB(B0, 0, 0); PG8_LDB(B1, 0, 1); PG8_SCHED; PG8_LDA(At, 0, 0); PG8_STAGE(PG8_SA(1, 1), a1 + hstepA, voffA);
;             PG8_WAIT_V(8); PG8_WAIT_L(0); PG8_BAR; PG8_MMA(0, 0, At, B0); PG8_MMA(0, 1, At, B1); PG8_BAR; PG8_SCHED;
;             PG8_LDA(At, 0, 1); PG8_STAGE(PG8_SB(0, 0), b2, voffB); PG8_STAGE(PG8_SB(0, 1), b2 + hstepB, voffB); PG8_STAGE(PG8_SA(0, 0), a2, voffA);
;             PG8_WAIT_V(8); PG8_WAIT_L(0); PG8_BAR; PG8_MMA(1, 0, At, B0); PG8_MMA(1, 1, At, B1); PG8_BAR; PG8_SCHED;
;             PG8_LDB(B0, 1, 0); PG8_LDB(B1, 1, 1); PG8_SCHED; PG8_LDA(At, 1, 0); PG8_STAGE(PG8_SA(0, 1), a2 + hstepA, voffA);
;             PG8_WAIT_V(8); PG8_WAIT_L(0); PG8_BAR; PG8_MMA(0, 0, At, B0); PG8_MMA(0, 1, At, B1); PG8_BAR; PG8_SCHED;
;             PG8_LDA(At, 1, 1); PG8_STAGE(PG8_SB(1, 0), b3, voffB); PG8_STAGE(PG8_SB(1, 1), b3 + hstepB, voffB); PG8_STAGE(PG8_SA(1, 0), a3, voffA);
;             PG8_WAIT_V(8); PG8_WAIT_L(0); PG8_BAR; PG8_MMA(1, 0, At, B0); PG8_MMA(1, 1, At, B1); PG8_BAR; PG8_SCHED;
	v_mfma_f32_16x16x32_bf16 v[54:57], v[130:133], v[162:165], v[54:57]
	v_mfma_f32_16x16x32_bf16 v[46:49], v[138:141], v[162:165], v[46:49]
	v_mfma_f32_16x16x32_bf16 v[38:41], v[130:133], v[170:173], v[38:41]
	v_mfma_f32_16x16x32_bf16 v[50:53], v[138:141], v[170:173], v[50:53]
	v_mfma_f32_16x16x32_bf16 v[18:21], v[130:133], v[190:193], v[18:21]
	v_mfma_f32_16x16x32_bf16 v[34:37], v[138:141], v[190:193], v[34:37]
	v_mfma_f32_16x16x32_bf16 v[22:25], v[130:133], v[206:209], v[22:25]
	v_mfma_f32_16x16x32_bf16 v[74:77], v[138:141], v[206:209], v[74:77]
	v_mfma_f32_16x16x32_bf16 v[54:57], v[134:137], v[166:169], v[54:57]
	v_mfma_f32_16x16x32_bf16 v[46:49], v[142:145], v[166:169], v[46:49]
	v_mfma_f32_16x16x32_bf16 v[38:41], v[134:137], v[174:177], v[38:41]
	v_mfma_f32_16x16x32_bf16 v[50:53], v[142:145], v[174:177], v[50:53]
	v_mfma_f32_16x16x32_bf16 v[18:21], v[134:137], v[202:205], v[18:21]
	v_mfma_f32_16x16x32_bf16 v[34:37], v[142:145], v[202:205], v[34:37]
	v_mfma_f32_16x16x32_bf16 v[22:25], v[134:137], v[210:213], v[22:25]
	v_mfma_f32_16x16x32_bf16 v[74:77], v[142:145], v[210:213], v[74:77]
	v_mfma_f32_16x16x32_bf16 v[58:61], v[146:149], v[162:165], v[58:61]
	v_mfma_f32_16x16x32_bf16 v[30:33], v[154:157], v[162:165], v[30:33]
	v_mfma_f32_16x16x32_bf16 v[42:45], v[146:149], v[170:173], v[42:45]
	v_mfma_f32_16x16x32_bf16 v[6:9], v[154:157], v[170:173], v[6:9]
	v_mfma_f32_16x16x32_bf16 v[26:29], v[146:149], v[190:193], v[26:29]
	v_mfma_f32_16x16x32_bf16 v[10:13], v[154:157], v[190:193], v[10:13]
	v_mfma_f32_16x16x32_bf16 v[14:17], v[146:149], v[206:209], v[14:17]
	v_mfma_f32_16x16x32_bf16 v[2:5], v[154:157], v[206:209], v[2:5]
	v_mfma_f32_16x16x32_bf16 v[58:61], v[150:153], v[166:169], v[58:61]
	v_mfma_f32_16x16x32_bf16 v[30:33], v[158:161], v[166:169], v[30:33]
	v_mfma_f32_16x16x32_bf16 v[42:45], v[150:153], v[174:177], v[42:45]
	v_mfma_f32_16x16x32_bf16 v[6:9], v[158:161], v[174:177], v[6:9]
	v_mfma_f32_16x16x32_bf16 v[26:29], v[150:153], v[202:205], v[26:29]
	v_mfma_f32_16x16x32_bf16 v[10:13], v[158:161], v[202:205], v[10:13]
	v_mfma_f32_16x16x32_bf16 v[14:17], v[150:153], v[210:213], v[14:17]
	v_mfma_f32_16x16x32_bf16 v[2:5], v[158:161], v[210:213], v[2:5]
	s_setprio 0
	s_barrier
	s_add_u32 s42, s42, 0x4000
	s_addc_u32 s43, s43, 0
	s_mov_b32 m0, s79
	v_lshl_add_u64 v[220:221], s[42:43], 0, v[178:179]
	global_load_lds_dwordx4 v[220:221], off
	s_mov_b32 m0, s87
	v_lshl_add_u64 v[220:221], s[42:43], 0, v[180:181]
	global_load_lds_dwordx4 v[220:221], off
	s_add_i32 s34, 0, 0x18000
	s_add_i32 s35, 0, 0x1c000
	v_add_u32_e32 v142, s34, v196
	v_add_u32_e32 v158, s35, v196
	ds_read_b128 v[130:133], v142
	ds_read_b128 v[134:137], v142 offset:1024
	ds_read_b128 v[138:141], v142 offset:2048
	ds_read_b128 v[142:145], v142 offset:3072
	ds_read_b128 v[146:149], v158
	ds_read_b128 v[150:153], v158 offset:1024
	ds_read_b128 v[154:157], v158 offset:2048
	ds_read_b128 v[158:161], v158 offset:3072
	ds_read_b128 v[162:165], v201 offset:32768
	ds_read_b128 v[166:169], v201 offset:33792
	ds_read_b128 v[170:173], v201 offset:34816
	ds_read_b128 v[174:177], v201 offset:35840
	ds_read_b128 v[190:193], v201 offset:36864
	ds_read_b128 v[202:205], v201 offset:37888
	ds_read_b128 v[206:209], v201 offset:38912
	ds_read_b128 v[210:213], v201 offset:39936
	s_setprio 1
	s_waitcnt vmcnt(8) lgkmcnt(0)
	s_barrier
	v_mfma_f32_16x16x32_bf16 v[126:129], v[130:133], v[162:165], v[126:129]
	v_mfma_f32_16x16x32_bf16 v[122:125], v[138:141], v[162:165], v[122:125]
	v_mfma_f32_16x16x32_bf16 v[118:121], v[130:133], v[170:173], v[118:121]
	v_mfma_f32_16x16x32_bf16 v[114:117], v[138:141], v[170:173], v[114:117]
	v_mfma_f32_16x16x32_bf16 v[110:113], v[130:133], v[190:193], v[110:113]
	v_mfma_f32_16x16x32_bf16 v[102:105], v[138:141], v[190:193], v[102:105]
	v_mfma_f32_16x16x32_bf16 v[90:93], v[130:133], v[206:209], v[90:93]
	v_mfma_f32_16x16x32_bf16 v[82:85], v[138:141], v[206:209], v[82:85]
	v_mfma_f32_16x16x32_bf16 v[126:129], v[134:137], v[166:169], v[126:129]
	v_mfma_f32_16x16x32_bf16 v[122:125], v[142:145], v[166:169], v[122:125]
	v_mfma_f32_16x16x32_bf16 v[118:121], v[134:137], v[174:177], v[118:121]
	v_mfma_f32_16x16x32_bf16 v[114:117], v[142:145], v[174:177], v[114:117]
	v_mfma_f32_16x16x32_bf16 v[110:113], v[134:137], v[202:205], v[110:113]
	v_mfma_f32_16x16x32_bf16 v[102:105], v[142:145], v[202:205], v[102:105]
	v_mfma_f32_16x16x32_bf16 v[90:93], v[134:137], v[210:213], v[90:93]
	v_mfma_f32_16x16x32_bf16 v[82:85], v[142:145], v[210:213], v[82:85]
	v_mfma_f32_16x16x32_bf16 v[106:109], v[146:149], v[162:165], v[106:109]
	v_mfma_f32_16x16x32_bf16 v[98:101], v[154:157], v[162:165], v[98:101]
	v_mfma_f32_16x16x32_bf16 v[94:97], v[146:149], v[170:173], v[94:97]
	v_mfma_f32_16x16x32_bf16 v[86:89], v[154:157], v[170:173], v[86:89]
	v_mfma_f32_16x16x32_bf16 v[70:73], v[146:149], v[190:193], v[70:73]
	v_mfma_f32_16x16x32_bf16 v[62:65], v[154:157], v[190:193], v[62:65]
	v_mfma_f32_16x16x32_bf16 v[78:81], v[146:149], v[206:209], v[78:81]
	v_mfma_f32_16x16x32_bf16 v[66:69], v[154:157], v[206:209], v[66:69]
	v_mfma_f32_16x16x32_bf16 v[106:109], v[150:153], v[166:169], v[106:109]
	v_mfma_f32_16x16x32_bf16 v[98:101], v[158:161], v[166:169], v[98:101]
	v_mfma_f32_16x16x32_bf16 v[94:97], v[150:153], v[174:177], v[94:97]
	v_mfma_f32_16x16x32_bf16 v[86:89], v[158:161], v[174:177], v[86:89]
	v_mfma_f32_16x16x32_bf16 v[70:73], v[150:153], v[202:205], v[70:73]
	v_mfma_f32_16x16x32_bf16 v[62:65], v[158:161], v[202:205], v[62:65]
	v_mfma_f32_16x16x32_bf16 v[78:81], v[150:153], v[210:213], v[78:81]
	v_mfma_f32_16x16x32_bf16 v[66:69], v[158:161], v[210:213], v[66:69]
	s_setprio 0
	s_barrier
; #define PG8_STAGE(bufoff, gbase, voff) do { _Pragma("unroll") for (int _i = 0; _i < 2; ++_i) \
;         __builtin_amdgcn_global_load_lds((const unsigned*)((const char*)(gbase) + (voff)[_i]), (LAS unsigned*)(lds + (bufoff) + ldsw + _i * 8192), 16, 0, 0); } while (0)
; #define PG8_LDA(dst, b, h) do { _Pragma("unroll") for (int m = 0; m < 4; ++m) _Pragma("unroll") for (int k = 0; k < 2; ++k) dst[m][k] = *(const LAS bf16x8*)(lds + PG8_SA(b, h) + aoff + m * 2048 + k * 1024); } while (0)
; #define PG8_MMA(ai, bj, At, Bt) do { __builtin_amdgcn_s_setprio(1); _Pragma("unroll") for (int m = 0; m < 4; ++m) _Pragma("unroll") for (int n = 0; n < 2; ++n) _Pragma("unroll") for (int k = 0; k < 2; ++k) \
;         acc[ai][bj][m][n] = __builtin_amdgcn_mfma_f32_16x16x32_bf16(Bt[n][k], At[m][k], acc[ai][bj][m][n], 0, 0, 0); __builtin_amdgcn_s_setprio(0); } while (0)
; #define PG8_WAIT_V(n) asm volatile("s_waitcnt vmcnt(" #n ")" ::: "memory")
; #define PG8_WAIT_L(n) asm volatile("s_waitcnt lgkmcnt(" #n ")" ::: "memory")
; #define PG8_BAR __builtin_amdgcn_s_barrier()
; #define PG8_SCHED __builtin_amdgcn_sched_barrier(0)
; template <class Epi, int AMODE>
; __device__ __forceinline__ void gemm_phase(LAS unsigned char* lds, const Gemm g, const StaticOrder& S, const Epi& E, int stagger_us, int tid_in) {
;     ...
;             PG8_LDA(At, 1, 1); PG8_STAGE(PG8_SB(1, 0), b3, voffB); PG8_STAGE(PG8_SB(1, 1), b3 + hstepB, voffB); PG8_STAGE(PG8_SA(1, 0), a3, voffA);
;             PG8_WAIT_V(8); PG8_WAIT_L(0); PG8_BAR; PG8_MMA(1, 0, At, B0); PG8_MMA(1, 1, At, B1); PG8_BAR; PG8_SCHED;
;         }
	s_add_i32 s34, s34, s91
	s_mov_b32 m0, s34
	v_lshl_add_u64 v[194:195], v[194:195], 0, s[74:75]
	global_load_lds_dwordx4 v[194:195], off
	s_add_i32 m0, s34, 0x2000
	s_add_u32 s6, s6, 0x80080
	v_lshl_add_u64 v[194:195], v[214:215], 0, s[74:75]
	s_addc_u32 s7, s7, 0
	s_add_i32 s34, s35, s91
	global_load_lds_dwordx4 v[194:195], off
	s_mov_b32 m0, s34
	v_lshl_add_u64 v[194:195], s[6:7], 0, v[0:1]
	global_load_lds_dwordx4 v[194:195], off
	s_add_i32 m0, s34, 0x2000
	v_lshl_add_u64 v[194:195], s[6:7], 0, v[182:183]
	global_load_lds_dwordx4 v[194:195], off
	s_mov_b32 m0, s67
	v_lshl_add_u64 v[194:195], v[216:217], 0, s[74:75]
	global_load_lds_dwordx4 v[194:195], off
	s_mov_b32 m0, s85
	v_lshl_add_u64 v[194:195], v[218:219], 0, s[74:75]
	global_load_lds_dwordx4 v[194:195], off
	ds_read_b128 v[162:165], v201 offset:49152
	ds_read_b128 v[166:169], v201 offset:50176
	ds_read_b128 v[170:173], v201 offset:51200
	ds_read_b128 v[174:177], v201 offset:52224
	ds_read_b128 v[190:193], v201 offset:53248
	ds_read_b128 v[202:205], v201 offset:54272
	ds_read_b128 v[206:209], v201 offset:55296
	ds_read_b128 v[210:213], v201 offset:56320
	s_setprio 1
	s_waitcnt vmcnt(8) lgkmcnt(0)
	s_barrier
	v_mfma_f32_16x16x32_bf16 v[54:57], v[130:133], v[162:165], v[54:57]
	v_mfma_f32_16x16x32_bf16 v[46:49], v[138:141], v[162:165], v[46:49]
	v_mfma_f32_16x16x32_bf16 v[38:41], v[130:133], v[170:173], v[38:41]
	v_mfma_f32_16x16x32_bf16 v[50:53], v[138:141], v[170:173], v[50:53]
	v_mfma_f32_16x16x32_bf16 v[18:21], v[130:133], v[190:193], v[18:21]
	v_mfma_f32_16x16x32_bf16 v[34:37], v[138:141], v[190:193], v[34:37]
	v_mfma_f32_16x16x32_bf16 v[22:25], v[130:133], v[206:209], v[22:25]
	v_mfma_f32_16x16x32_bf16 v[74:77], v[138:141], v[206:209], v[74:77]
	v_mfma_f32_16x16x32_bf16 v[54:57], v[134:137], v[166:169], v[54:57]
	v_mfma_f32_16x16x32_bf16 v[46:49], v[142:145], v[166:169], v[46:49]
	v_mfma_f32_16x16x32_bf16 v[38:41], v[134:137], v[174:177], v[38:41]
	v_mfma_f32_16x16x32_bf16 v[50:53], v[142:145], v[174:177], v[50:53]
	v_mfma_f32_16x16x32_bf16 v[18:21], v[134:137], v[202:205], v[18:21]
	v_mfma_f32_16x16x32_bf16 v[34:37], v[142:145], v[202:205], v[34:37]
	v_mfma_f32_16x16x32_bf16 v[22:25], v[134:137], v[210:213], v[22:25]
	v_mfma_f32_16x16x32_bf16 v[74:77], v[142:145], v[210:213], v[74:77]
	v_mfma_f32_16x16x32_bf16 v[58:61], v[146:149], v[162:165], v[58:61]
	v_mfma_f32_16x16x32_bf16 v[30:33], v[154:157], v[162:165], v[30:33]
	v_mfma_f32_16x16x32_bf16 v[42:45], v[146:149], v[170:173], v[42:45]
	v_mfma_f32_16x16x32_bf16 v[6:9], v[154:157], v[170:173], v[6:9]
	v_mfma_f32_16x16x32_bf16 v[26:29], v[146:149], v[190:193], v[26:29]
	v_mfma_f32_16x16x32_bf16 v[10:13], v[154:157], v[190:193], v[10:13]
	v_mfma_f32_16x16x32_bf16 v[14:17], v[146:149], v[206:209], v[14:17]
	v_mfma_f32_16x16x32_bf16 v[2:5], v[154:157], v[206:209], v[2:5]
	v_mfma_f32_16x16x32_bf16 v[58:61], v[150:153], v[166:169], v[58:61]
	v_mfma_f32_16x16x32_bf16 v[30:33], v[158:161], v[166:169], v[30:33]
	v_mfma_f32_16x16x32_bf16 v[42:45], v[150:153], v[174:177], v[42:45]
	v_mfma_f32_16x16x32_bf16 v[6:9], v[158:161], v[174:177], v[6:9]
	v_mfma_f32_16x16x32_bf16 v[26:29], v[150:153], v[202:205], v[26:29]
	v_mfma_f32_16x16x32_bf16 v[10:13], v[158:161], v[202:205], v[10:13]
	v_mfma_f32_16x16x32_bf16 v[14:17], v[150:153], v[210:213], v[14:17]
	v_mfma_f32_16x16x32_bf16 v[2:5], v[158:161], v[210:213], v[2:5]
	s_setprio 0
	s_barrier
	s_add_i32 s31, s31, 2
	s_add_u32 s29, s29, 0x100
	s_addc_u32 s30, s30, 0
	s_cmp_gt_u32 s31, 29
	s_mov_b64 s[44:45], s[4:5]
	s_cbranch_scc0 .LBB0_1299
	s_and_b64 vcc, exec, s[48:49]
	s_cbranch_vccz .LBB0_1302
	s_barrier

; #define PG8_STAGE(bufoff, gbase, voff) do { _Pragma("unroll") for (int _i = 0; _i < 2; ++_i) \
;         __builtin_amdgcn_global_load_lds((const unsigned*)((const char*)(gbase) + (voff)[_i]), (LAS unsigned*)(lds + (bufoff) + ldsw + _i * 8192), 16, 0, 0); } while (0)
; #define PG8_LDA(dst, b, h) do { _Pragma("unroll") for (int m = 0; m < 4; ++m) _Pragma("unroll") for (int k = 0; k < 2; ++k) dst[m][k] = *(const LAS bf16x8*)(lds + PG8_SA(b, h) + aoff + m * 2048 + k * 1024); } while (0)
; #define PG8_LDB(dst, b, h) do { _Pragma("unroll") for (int n = 0; n < 2; ++n) _Pragma("unroll") for (int k = 0; k < 2; ++k) dst[n][k] = *(const LAS bf16x8*)(lds + PG8_SB(b, h) + boff + n * 2048 + k * 1024); } while (0)
; #define PG8_MMA(ai, bj, At, Bt) do { __builtin_amdgcn_s_setprio(1); _Pragma("unroll") for (int m = 0; m < 4; ++m) _Pragma("unroll") for (int n = 0; n < 2; ++n) _Pragma("unroll") for (int k = 0; k < 2; ++k) \
;         acc[ai][bj][m][n] = __builtin_amdgcn_mfma_f32_16x16x32_bf16(Bt[n][k], At[m][k], acc[ai][bj][m][n], 0, 0, 0); __builtin_amdgcn_s_setprio(0); } while (0)
; #define PG8_BAR __builtin_amdgcn_s_barrier()
; template <class Epi, int AMODE>
; __device__ __forceinline__ void gemm_phase(LAS unsigned char* lds, const Gemm g, const StaticOrder& S, const Epi& E, int stagger_us, int tid_in) {
;     ...
;         const bool has_next = S.next(ui + 1, nxt);
;         const char* nA = has_next ? Abase + (size_t)nxt.pm * tstepA : cA; const char* nB = has_next ? (const char*)g.Bt + (size_t)nxt.pn * tstepB : cB;
;         for (int t = 0; t < nt; t += 2) {
;             const bool last = (t == nt - 2);
;             const char* a1 = cA + (size_t)(t + 1) * kstep;
;             const char* a2 = last ? nA : cA + (size_t)(t + 2) * kstep; const char* b2 = last ? nB : cB + (size_t)(t + 2) * kstep;
;             const char* a3 = a2 + kstep; const char* b3 = b2 + kstep;
;             PG8_LDB(B0, 0, 0); PG8_LDB(B1, 0, 1); PG8_SCHED; PG8_LDA(At, 0, 0); PG8_STAGE(PG8_SA(1, 1), a1 + hstepA, voffA);
;             PG8_WAIT_V(8); PG8_WAIT_L(0); PG8_BAR; PG8_MMA(0, 0, At, B0); PG8_MMA(0, 1, At, B1); PG8_BAR; PG8_SCHED;
;             PG8_LDA(At, 0, 1); PG8_STAGE(PG8_SB(0, 0), b2, voffB); PG8_STAGE(PG8_SB(0, 1), b2 + hstepB, voffB); PG8_STAGE(PG8_SA(0, 0), a2, voffA);
;             PG8_WAIT_V(8); PG8_WAIT_L(0); PG8_BAR; PG8_MMA(1, 0, At, B0); PG8_MMA(1, 1, At, B1); PG8_BAR; PG8_SCHED;
.LBB0_1476:
	s_add_i32 m0, s13, 0xc000
	v_lshl_add_u64 v[206:207], s[54:55], 0, v[148:149]
	global_load_lds_dwordx4 v[206:207], off
	s_add_i32 m0, s13, 0xe000
	v_lshl_add_u64 v[206:207], s[54:55], 0, v[150:151]
	global_load_lds_dwordx4 v[206:207], off
	s_add_u32 s4, s54, 0x100
	s_addc_u32 s5, s55, 0
	s_add_i32 s30, 0, 0x10000
	s_cmpk_eq_i32 s29, 0x52
	s_cselect_b32 s57, s41, s5
	s_cselect_b32 s56, s40, s4
	s_cselect_b32 s7, s53, s28
	s_cselect_b32 s6, s52, s27
	s_add_i32 s34, 0, 0x14000
	v_add_u32_e32 v102, s30, v162
	v_add_u32_e32 v165, s34, v162
	ds_read_b128 v[66:69], v102
	ds_read_b128 v[70:73], v102 offset:1024
	ds_read_b128 v[74:77], v102 offset:2048
	ds_read_b128 v[102:105], v102 offset:3072
	ds_read_b128 v[152:155], v165
	ds_read_b128 v[156:159], v165 offset:1024
	ds_read_b128 v[166:169], v165 offset:2048
	ds_read_b128 v[170:173], v165 offset:3072
	ds_read_b128 v[174:177], v164
	ds_read_b128 v[178:181], v164 offset:1024
	ds_read_b128 v[182:185], v164 offset:2048
	ds_read_b128 v[186:189], v164 offset:3072
	ds_read_b128 v[190:193], v164 offset:4096
	ds_read_b128 v[194:197], v164 offset:5120
	ds_read_b128 v[198:201], v164 offset:6144
	ds_read_b128 v[202:205], v164 offset:7168
	s_setprio 1
	s_waitcnt vmcnt(8) lgkmcnt(0)
	s_barrier
	v_mfma_f32_16x16x32_bf16 v[142:145], v[66:69], v[174:177], v[142:145]
	v_mfma_f32_16x16x32_bf16 v[138:141], v[74:77], v[174:177], v[138:141]
	v_mfma_f32_16x16x32_bf16 v[134:137], v[66:69], v[182:185], v[134:137]
	v_mfma_f32_16x16x32_bf16 v[130:133], v[74:77], v[182:185], v[130:133]
	v_mfma_f32_16x16x32_bf16 v[110:113], v[66:69], v[190:193], v[110:113]
	v_mfma_f32_16x16x32_bf16 v[106:109], v[74:77], v[190:193], v[106:109]
	v_mfma_f32_16x16x32_bf16 v[98:101], v[66:69], v[198:201], v[98:101]
	v_mfma_f32_16x16x32_bf16 v[94:97], v[74:77], v[198:201], v[94:97]
	v_mfma_f32_16x16x32_bf16 v[142:145], v[70:73], v[178:181], v[142:145]
	v_mfma_f32_16x16x32_bf16 v[138:141], v[102:105], v[178:181], v[138:141]
	v_mfma_f32_16x16x32_bf16 v[134:137], v[70:73], v[186:189], v[134:137]
	v_mfma_f32_16x16x32_bf16 v[130:133], v[102:105], v[186:189], v[130:133]
	v_mfma_f32_16x16x32_bf16 v[110:113], v[70:73], v[194:197], v[110:113]
	v_mfma_f32_16x16x32_bf16 v[106:109], v[102:105], v[194:197], v[106:109]
	v_mfma_f32_16x16x32_bf16 v[98:101], v[70:73], v[202:205], v[98:101]
	v_mfma_f32_16x16x32_bf16 v[94:97], v[102:105], v[202:205], v[94:97]
	v_mfma_f32_16x16x32_bf16 v[126:129], v[152:155], v[174:177], v[126:129]
	v_mfma_f32_16x16x32_bf16 v[122:125], v[166:169], v[174:177], v[122:125]
	v_mfma_f32_16x16x32_bf16 v[118:121], v[152:155], v[182:185], v[118:121]
	v_mfma_f32_16x16x32_bf16 v[114:117], v[166:169], v[182:185], v[114:117]
	v_mfma_f32_16x16x32_bf16 v[90:93], v[152:155], v[190:193], v[90:93]
	v_mfma_f32_16x16x32_bf16 v[86:89], v[166:169], v[190:193], v[86:89]
	v_mfma_f32_16x16x32_bf16 v[82:85], v[152:155], v[198:201], v[82:85]
	v_mfma_f32_16x16x32_bf16 v[78:81], v[166:169], v[198:201], v[78:81]
	v_mfma_f32_16x16x32_bf16 v[126:129], v[156:159], v[178:181], v[126:129]
	v_mfma_f32_16x16x32_bf16 v[122:125], v[170:173], v[178:181], v[122:125]
	v_mfma_f32_16x16x32_bf16 v[118:121], v[156:159], v[186:189], v[118:121]
	v_mfma_f32_16x16x32_bf16 v[114:117], v[170:173], v[186:189], v[114:117]
	v_mfma_f32_16x16x32_bf16 v[90:93], v[156:159], v[194:197], v[90:93]
	v_mfma_f32_16x16x32_bf16 v[86:89], v[170:173], v[194:197], v[86:89]
	v_mfma_f32_16x16x32_bf16 v[82:85], v[156:159], v[202:205], v[82:85]
	v_mfma_f32_16x16x32_bf16 v[78:81], v[170:173], v[202:205], v[78:81]
	s_setprio 0
	s_barrier
	s_add_i32 s30, s30, s12
	s_mov_b32 m0, s30
	v_lshl_add_u64 v[206:207], s[6:7], 0, v[0:1]
	global_load_lds_dwordx4 v[206:207], off
	s_add_i32 m0, s30, 0x2000
	s_add_u32 s30, s6, 0x158000
	v_lshl_add_u64 v[208:209], s[6:7], 0, v[146:147]
	s_addc_u32 s31, s7, 0
	s_add_i32 s34, s34, s12
	global_load_lds_dwordx4 v[208:209], off
	v_lshl_add_u64 v[210:211], s[30:31], 0, v[0:1]
	s_mov_b32 m0, s34
	v_lshl_add_u64 v[212:213], s[56:57], 0, v[146:147]
	global_load_lds_dwordx4 v[210:211], off
	s_add_i32 m0, s34, 0x2000
	v_lshl_add_u64 v[210:211], s[30:31], 0, v[146:147]
	global_load_lds_dwordx4 v[210:211], off
	s_mov_b32 m0, s13
	v_lshl_add_u64 v[210:211], s[56:57], 0, v[0:1]
	global_load_lds_dwordx4 v[210:211], off
	s_mov_b32 m0, s24
	s_nop 0
	global_load_lds_dwordx4 v[212:213], off
	ds_read_b128 v[174:177], v164 offset:16384
	ds_read_b128 v[178:181], v164 offset:17408
	ds_read_b128 v[182:185], v164 offset:18432
	ds_read_b128 v[186:189], v164 offset:19456
	ds_read_b128 v[190:193], v164 offset:20480
	ds_read_b128 v[194:197], v164 offset:21504
	ds_read_b128 v[198:201], v164 offset:22528
	ds_read_b128 v[202:205], v164 offset:23552
	s_setprio 1
	s_waitcnt vmcnt(8) lgkmcnt(0)
	s_barrier
; #define PG8_STAGE(bufoff, gbase, voff) do { _Pragma("unroll") for (int _i = 0; _i < 2; ++_i) \
;         __builtin_amdgcn_global_load_lds((const unsigned*)((const char*)(gbase) + (voff)[_i]), (LAS unsigned*)(lds + (bufoff) + ldsw + _i * 8192), 16, 0, 0); } while (0)
; #define PG8_LDA(dst, b, h) do { _Pragma("unroll") for (int m = 0; m < 4; ++m) _Pragma("unroll") for (int k = 0; k < 2; ++k) dst[m][k] = *(const LAS bf16x8*)(lds + PG8_SA(b, h) + aoff + m * 2048 + k * 1024); } while (0)
; #define PG8_LDB(dst, b, h) do { _Pragma("unroll") for (int n = 0; n < 2; ++n) _Pragma("unroll") for (int k = 0; k < 2; ++k) dst[n][k] = *(const LAS bf16x8*)(lds + PG8_SB(b, h) + boff + n * 2048 + k * 1024); } while (0)
; #define PG8_MMA(ai, bj, At, Bt) do { __builtin_amdgcn_s_setprio(1); _Pragma("unroll") for (int m = 0; m < 4; ++m) _Pragma("unroll") for (int n = 0; n < 2; ++n) _Pragma("unroll") for (int k = 0; k < 2; ++k) \
;         acc[ai][bj][m][n] = __builtin_amdgcn_mfma_f32_16x16x32_bf16(Bt[n][k], At[m][k], acc[ai][bj][m][n], 0, 0, 0); __builtin_amdgcn_s_setprio(0); } while (0)
; #define PG8_WAIT_V(n) asm volatile("s_waitcnt vmcnt(" #n ")" ::: "memory")
; #define PG8_WAIT_L(n) asm volatile("s_waitcnt lgkmcnt(" #n ")" ::: "memory")
; #define PG8_BAR __builtin_amdgcn_s_barrier()
; #define PG8_SCHED __builtin_amdgcn_sched_barrier(0)
; template <class Epi, int AMODE>
; __device__ __forceinline__ void gemm_phase(LAS unsigned char* lds, const Gemm g, const StaticOrder& S, const Epi& E, int stagger_us, int tid_in) {
;     ...
;             PG8_WAIT_V(8); PG8_WAIT_L(0); PG8_BAR; PG8_MMA(1, 0, At, B0); PG8_MMA(1, 1, At, B1); PG8_BAR; PG8_SCHED;
;             PG8_LDB(B0, 1, 0); PG8_LDB(B1, 1, 1); PG8_SCHED; PG8_LDA(At, 1, 0); PG8_STAGE(PG8_SA(0, 1), a2 + hstepA, voffA);
;             PG8_WAIT_V(8); PG8_WAIT_L(0); PG8_BAR; PG8_MMA(0, 0, At, B0); PG8_MMA(0, 1, At, B1); PG8_BAR; PG8_SCHED;
	v_mfma_f32_16x16x32_bf16 v[62:65], v[66:69], v[174:177], v[62:65]
	v_mfma_f32_16x16x32_bf16 v[58:61], v[74:77], v[174:177], v[58:61]
	v_mfma_f32_16x16x32_bf16 v[54:57], v[66:69], v[182:185], v[54:57]
	v_mfma_f32_16x16x32_bf16 v[50:53], v[74:77], v[182:185], v[50:53]
	v_mfma_f32_16x16x32_bf16 v[30:33], v[66:69], v[190:193], v[30:33]
	v_mfma_f32_16x16x32_bf16 v[26:29], v[74:77], v[190:193], v[26:29]
	v_mfma_f32_16x16x32_bf16 v[22:25], v[66:69], v[198:201], v[22:25]
	v_mfma_f32_16x16x32_bf16 v[10:13], v[74:77], v[198:201], v[10:13]
	v_mfma_f32_16x16x32_bf16 v[62:65], v[70:73], v[178:181], v[62:65]
	v_mfma_f32_16x16x32_bf16 v[58:61], v[102:105], v[178:181], v[58:61]
	v_mfma_f32_16x16x32_bf16 v[54:57], v[70:73], v[186:189], v[54:57]
	v_mfma_f32_16x16x32_bf16 v[50:53], v[102:105], v[186:189], v[50:53]
	v_mfma_f32_16x16x32_bf16 v[30:33], v[70:73], v[194:197], v[30:33]
	v_mfma_f32_16x16x32_bf16 v[26:29], v[102:105], v[194:197], v[26:29]
	v_mfma_f32_16x16x32_bf16 v[22:25], v[70:73], v[202:205], v[22:25]
	v_mfma_f32_16x16x32_bf16 v[10:13], v[102:105], v[202:205], v[10:13]
	v_mfma_f32_16x16x32_bf16 v[46:49], v[152:155], v[174:177], v[46:49]
	v_mfma_f32_16x16x32_bf16 v[42:45], v[166:169], v[174:177], v[42:45]
	v_mfma_f32_16x16x32_bf16 v[38:41], v[152:155], v[182:185], v[38:41]
	v_mfma_f32_16x16x32_bf16 v[34:37], v[166:169], v[182:185], v[34:37]
	v_mfma_f32_16x16x32_bf16 v[18:21], v[152:155], v[190:193], v[18:21]
	v_mfma_f32_16x16x32_bf16 v[14:17], v[166:169], v[190:193], v[14:17]
	v_mfma_f32_16x16x32_bf16 v[6:9], v[152:155], v[198:201], v[6:9]
	v_mfma_f32_16x16x32_bf16 v[2:5], v[166:169], v[198:201], v[2:5]
	v_mfma_f32_16x16x32_bf16 v[46:49], v[156:159], v[178:181], v[46:49]
	v_mfma_f32_16x16x32_bf16 v[42:45], v[170:173], v[178:181], v[42:45]
	v_mfma_f32_16x16x32_bf16 v[38:41], v[156:159], v[186:189], v[38:41]
	v_mfma_f32_16x16x32_bf16 v[34:37], v[170:173], v[186:189], v[34:37]
	v_mfma_f32_16x16x32_bf16 v[18:21], v[156:159], v[194:197], v[18:21]
	v_mfma_f32_16x16x32_bf16 v[14:17], v[170:173], v[194:197], v[14:17]
	v_mfma_f32_16x16x32_bf16 v[6:9], v[156:159], v[202:205], v[6:9]
	v_mfma_f32_16x16x32_bf16 v[2:5], v[170:173], v[202:205], v[2:5]
	s_setprio 0
	s_barrier
	s_add_u32 s30, s56, 0x158000
	s_addc_u32 s31, s57, 0
	s_mov_b32 m0, s25
	v_lshl_add_u64 v[214:215], s[30:31], 0, v[0:1]
	global_load_lds_dwordx4 v[214:215], off
	s_mov_b32 m0, s66
	v_lshl_add_u64 v[214:215], s[30:31], 0, v[146:147]
	global_load_lds_dwordx4 v[214:215], off
	s_add_i32 s34, 0, 0x18000
	s_add_i32 s35, 0, 0x1c000
	v_add_u32_e32 v102, s34, v162
	v_add_u32_e32 v165, s35, v162
	ds_read_b128 v[66:69], v102
	ds_read_b128 v[70:73], v102 offset:1024
	ds_read_b128 v[74:77], v102 offset:2048
	ds_read_b128 v[102:105], v102 offset:3072
	ds_read_b128 v[152:155], v165
	ds_read_b128 v[156:159], v165 offset:1024
	ds_read_b128 v[166:169], v165 offset:2048
	ds_read_b128 v[170:173], v165 offset:3072
	ds_read_b128 v[174:177], v164 offset:32768
	ds_read_b128 v[178:181], v164 offset:33792
	ds_read_b128 v[182:185], v164 offset:34816
	ds_read_b128 v[186:189], v164 offset:35840
	ds_read_b128 v[190:193], v164 offset:36864
	ds_read_b128 v[194:197], v164 offset:37888
	ds_read_b128 v[198:201], v164 offset:38912
	ds_read_b128 v[202:205], v164 offset:39936
	s_setprio 1
	s_waitcnt vmcnt(8) lgkmcnt(0)
	s_barrier
	v_mfma_f32_16x16x32_bf16 v[142:145], v[66:69], v[174:177], v[142:145]
	v_mfma_f32_16x16x32_bf16 v[138:141], v[74:77], v[174:177], v[138:141]
	v_mfma_f32_16x16x32_bf16 v[134:137], v[66:69], v[182:185], v[134:137]
	v_mfma_f32_16x16x32_bf16 v[130:133], v[74:77], v[182:185], v[130:133]
	v_mfma_f32_16x16x32_bf16 v[110:113], v[66:69], v[190:193], v[110:113]
	v_mfma_f32_16x16x32_bf16 v[106:109], v[74:77], v[190:193], v[106:109]
	v_mfma_f32_16x16x32_bf16 v[98:101], v[66:69], v[198:201], v[98:101]
	v_mfma_f32_16x16x32_bf16 v[94:97], v[74:77], v[198:201], v[94:97]
	v_mfma_f32_16x16x32_bf16 v[142:145], v[70:73], v[178:181], v[142:145]
	v_mfma_f32_16x16x32_bf16 v[138:141], v[102:105], v[178:181], v[138:141]
	v_mfma_f32_16x16x32_bf16 v[134:137], v[70:73], v[186:189], v[134:137]
	v_mfma_f32_16x16x32_bf16 v[130:133], v[102:105], v[186:189], v[130:133]
	v_mfma_f32_16x16x32_bf16 v[110:113], v[70:73], v[194:197], v[110:113]
	v_mfma_f32_16x16x32_bf16 v[106:109], v[102:105], v[194:197], v[106:109]
	v_mfma_f32_16x16x32_bf16 v[98:101], v[70:73], v[202:205], v[98:101]
	v_mfma_f32_16x16x32_bf16 v[94:97], v[102:105], v[202:205], v[94:97]
	v_mfma_f32_16x16x32_bf16 v[126:129], v[152:155], v[174:177], v[126:129]
	v_mfma_f32_16x16x32_bf16 v[122:125], v[166:169], v[174:177], v[122:125]
	v_mfma_f32_16x16x32_bf16 v[118:121], v[152:155], v[182:185], v[118:121]
	v_mfma_f32_16x16x32_bf16 v[114:117], v[166:169], v[182:185], v[114:117]
	v_mfma_f32_16x16x32_bf16 v[90:93], v[152:155], v[190:193], v[90:93]
	v_mfma_f32_16x16x32_bf16 v[86:89], v[166:169], v[190:193], v[86:89]
	v_mfma_f32_16x16x32_bf16 v[82:85], v[152:155], v[198:201], v[82:85]
	v_mfma_f32_16x16x32_bf16 v[78:81], v[166:169], v[198:201], v[78:81]
	v_mfma_f32_16x16x32_bf16 v[126:129], v[156:159], v[178:181], v[126:129]
	v_mfma_f32_16x16x32_bf16 v[122:125], v[170:173], v[178:181], v[122:125]
	v_mfma_f32_16x16x32_bf16 v[118:121], v[156:159], v[186:189], v[118:121]
	v_mfma_f32_16x16x32_bf16 v[114:117], v[170:173], v[186:189], v[114:117]
	v_mfma_f32_16x16x32_bf16 v[90:93], v[156:159], v[194:197], v[90:93]
	v_mfma_f32_16x16x32_bf16 v[86:89], v[170:173], v[194:197], v[86:89]
	v_mfma_f32_16x16x32_bf16 v[82:85], v[156:159], v[202:205], v[82:85]
	v_mfma_f32_16x16x32_bf16 v[78:81], v[170:173], v[202:205], v[78:81]
	s_setprio 0
	s_barrier
; #define PG8_STAGE(bufoff, gbase, voff) do { _Pragma("unroll") for (int _i = 0; _i < 2; ++_i) \
;         __builtin_amdgcn_global_load_lds((const unsigned*)((const char*)(gbase) + (voff)[_i]), (LAS unsigned*)(lds + (bufoff) + ldsw + _i * 8192), 16, 0, 0); } while (0)
; #define PG8_LDA(dst, b, h) do { _Pragma("unroll") for (int m = 0; m < 4; ++m) _Pragma("unroll") for (int k = 0; k < 2; ++k) dst[m][k] = *(const LAS bf16x8*)(lds + PG8_SA(b, h) + aoff + m * 2048 + k * 1024); } while (0)
; #define PG8_MMA(ai, bj, At, Bt) do { __builtin_amdgcn_s_setprio(1); _Pragma("unroll") for (int m = 0; m < 4; ++m) _Pragma("unroll") for (int n = 0; n < 2; ++n) _Pragma("unroll") for (int k = 0; k < 2; ++k) \
;         acc[ai][bj][m][n] = __builtin_amdgcn_mfma_f32_16x16x32_bf16(Bt[n][k], At[m][k], acc[ai][bj][m][n], 0, 0, 0); __builtin_amdgcn_s_setprio(0); } while (0)
; #define PG8_WAIT_V(n) asm volatile("s_waitcnt vmcnt(" #n ")" ::: "memory")
; #define PG8_WAIT_L(n) asm volatile("s_waitcnt lgkmcnt(" #n ")" ::: "memory")
; #define PG8_BAR __builtin_amdgcn_s_barrier()
; #define PG8_SCHED __builtin_amdgcn_sched_barrier(0)
; template <class Epi, int AMODE>
; __device__ __forceinline__ void gemm_phase(LAS unsigned char* lds, const Gemm g, const StaticOrder& S, const Epi& E, int stagger_us, int tid_in) {
;     ...
;             PG8_LDA(At, 1, 1); PG8_STAGE(PG8_SB(1, 0), b3, voffB); PG8_STAGE(PG8_SB(1, 1), b3 + hstepB, voffB); PG8_STAGE(PG8_SA(1, 0), a3, voffA);
;             PG8_WAIT_V(8); PG8_WAIT_L(0); PG8_BAR; PG8_MMA(1, 0, At, B0); PG8_MMA(1, 1, At, B1); PG8_BAR; PG8_SCHED;
;         }
	s_add_i32 s30, s34, s12
	s_mov_b32 m0, s30
	v_lshl_add_u64 v[206:207], v[206:207], 0, s[74:75]
	global_load_lds_dwordx4 v[206:207], off
	s_add_i32 m0, s30, 0x2000
	s_add_u32 s6, s6, 0x158080
	v_lshl_add_u64 v[206:207], v[208:209], 0, s[74:75]
	s_addc_u32 s7, s7, 0
	s_add_i32 s30, s35, s12
	global_load_lds_dwordx4 v[206:207], off
	s_mov_b32 m0, s30
	v_lshl_add_u64 v[206:207], s[6:7], 0, v[0:1]
	global_load_lds_dwordx4 v[206:207], off
	s_add_i32 m0, s30, 0x2000
	v_lshl_add_u64 v[206:207], s[6:7], 0, v[146:147]
	global_load_lds_dwordx4 v[206:207], off
	s_mov_b32 m0, s67
	v_lshl_add_u64 v[206:207], v[210:211], 0, s[74:75]
	global_load_lds_dwordx4 v[206:207], off
	s_mov_b32 m0, s69
	v_lshl_add_u64 v[206:207], v[212:213], 0, s[74:75]
	global_load_lds_dwordx4 v[206:207], off
	ds_read_b128 v[174:177], v164 offset:49152
	ds_read_b128 v[178:181], v164 offset:50176
	ds_read_b128 v[182:185], v164 offset:51200
	ds_read_b128 v[186:189], v164 offset:52224
	ds_read_b128 v[190:193], v164 offset:53248
	ds_read_b128 v[194:197], v164 offset:54272
	ds_read_b128 v[198:201], v164 offset:55296
	ds_read_b128 v[202:205], v164 offset:56320
	s_setprio 1
	s_waitcnt vmcnt(8) lgkmcnt(0)
	s_barrier
	v_mfma_f32_16x16x32_bf16 v[62:65], v[66:69], v[174:177], v[62:65]
	v_mfma_f32_16x16x32_bf16 v[58:61], v[74:77], v[174:177], v[58:61]
	v_mfma_f32_16x16x32_bf16 v[54:57], v[66:69], v[182:185], v[54:57]
	v_mfma_f32_16x16x32_bf16 v[50:53], v[74:77], v[182:185], v[50:53]
	v_mfma_f32_16x16x32_bf16 v[30:33], v[66:69], v[190:193], v[30:33]
	v_mfma_f32_16x16x32_bf16 v[26:29], v[74:77], v[190:193], v[26:29]
	v_mfma_f32_16x16x32_bf16 v[22:25], v[66:69], v[198:201], v[22:25]
	v_mfma_f32_16x16x32_bf16 v[10:13], v[74:77], v[198:201], v[10:13]
	v_mfma_f32_16x16x32_bf16 v[62:65], v[70:73], v[178:181], v[62:65]
	v_mfma_f32_16x16x32_bf16 v[58:61], v[102:105], v[178:181], v[58:61]
	v_mfma_f32_16x16x32_bf16 v[54:57], v[70:73], v[186:189], v[54:57]
	v_mfma_f32_16x16x32_bf16 v[50:53], v[102:105], v[186:189], v[50:53]
	v_mfma_f32_16x16x32_bf16 v[30:33], v[70:73], v[194:197], v[30:33]
	v_mfma_f32_16x16x32_bf16 v[26:29], v[102:105], v[194:197], v[26:29]
	v_mfma_f32_16x16x32_bf16 v[22:25], v[70:73], v[202:205], v[22:25]
	v_mfma_f32_16x16x32_bf16 v[10:13], v[102:105], v[202:205], v[10:13]
	v_mfma_f32_16x16x32_bf16 v[46:49], v[152:155], v[174:177], v[46:49]
	v_mfma_f32_16x16x32_bf16 v[42:45], v[166:169], v[174:177], v[42:45]
	v_mfma_f32_16x16x32_bf16 v[38:41], v[152:155], v[182:185], v[38:41]
	v_mfma_f32_16x16x32_bf16 v[34:37], v[166:169], v[182:185], v[34:37]
	v_mfma_f32_16x16x32_bf16 v[18:21], v[152:155], v[190:193], v[18:21]
	v_mfma_f32_16x16x32_bf16 v[14:17], v[166:169], v[190:193], v[14:17]
	v_mfma_f32_16x16x32_bf16 v[6:9], v[152:155], v[198:201], v[6:9]
	v_mfma_f32_16x16x32_bf16 v[2:5], v[166:169], v[198:201], v[2:5]
	v_mfma_f32_16x16x32_bf16 v[46:49], v[156:159], v[178:181], v[46:49]
	v_mfma_f32_16x16x32_bf16 v[42:45], v[170:173], v[178:181], v[42:45]
	v_mfma_f32_16x16x32_bf16 v[38:41], v[156:159], v[186:189], v[38:41]
	v_mfma_f32_16x16x32_bf16 v[34:37], v[170:173], v[186:189], v[34:37]
	v_mfma_f32_16x16x32_bf16 v[18:21], v[156:159], v[194:197], v[18:21]
	v_mfma_f32_16x16x32_bf16 v[14:17], v[170:173], v[194:197], v[14:17]
	v_mfma_f32_16x16x32_bf16 v[6:9], v[156:159], v[202:205], v[6:9]
	v_mfma_f32_16x16x32_bf16 v[2:5], v[170:173], v[202:205], v[2:5]
	s_setprio 0
	s_barrier
	s_add_i32 s29, s29, 2
	s_add_u32 s27, s27, 0x100
	s_addc_u32 s28, s28, 0
	s_cmpk_gt_u32 s29, 0x53
	s_mov_b64 s[54:55], s[4:5]
	s_cbranch_scc0 .LBB0_1476
	s_and_b64 vcc, exec, s[46:47]
	s_cbranch_vccz .LBB0_1479
	s_barrier

; #define PG8_STAGE(bufoff, gbase, voff) do { _Pragma("unroll") for (int _i = 0; _i < 2; ++_i) \
;         __builtin_amdgcn_global_load_lds((const unsigned*)((const char*)(gbase) + (voff)[_i]), (LAS unsigned*)(lds + (bufoff) + ldsw + _i * 8192), 16, 0, 0); } while (0)
; #define PG8_LDA(dst, b, h) do { _Pragma("unroll") for (int m = 0; m < 4; ++m) _Pragma("unroll") for (int k = 0; k < 2; ++k) dst[m][k] = *(const LAS bf16x8*)(lds + PG8_SA(b, h) + aoff + m * 2048 + k * 1024); } while (0)
; #define PG8_LDB(dst, b, h) do { _Pragma("unroll") for (int n = 0; n < 2; ++n) _Pragma("unroll") for (int k = 0; k < 2; ++k) dst[n][k] = *(const LAS bf16x8*)(lds + PG8_SB(b, h) + boff + n * 2048 + k * 1024); } while (0)
; #define PG8_MMA(ai, bj, At, Bt) do { __builtin_amdgcn_s_setprio(1); _Pragma("unroll") for (int m = 0; m < 4; ++m) _Pragma("unroll") for (int n = 0; n < 2; ++n) _Pragma("unroll") for (int k = 0; k < 2; ++k) \
;         acc[ai][bj][m][n] = __builtin_amdgcn_mfma_f32_16x16x32_bf16(Bt[n][k], At[m][k], acc[ai][bj][m][n], 0, 0, 0); __builtin_amdgcn_s_setprio(0); } while (0)
; #define PG8_BAR __builtin_amdgcn_s_barrier()
; template <class Epi, int AMODE>
; __device__ __forceinline__ void gemm_phase(LAS unsigned char* lds, const Gemm g, const StaticOrder& S, const Epi& E, int stagger_us, int tid_in) {
;     ...
;         const bool has_next = S.next(ui + 1, nxt);
;         const char* nA = has_next ? Abase + (size_t)nxt.pm * tstepA : cA; const char* nB = has_next ? (const char*)g.Bt + (size_t)nxt.pn * tstepB : cB;
;         for (int t = 0; t < nt; t += 2) {
;             const bool last = (t == nt - 2);
;             const char* a1 = cA + (size_t)(t + 1) * kstep;
;             const char* a2 = last ? nA : cA + (size_t)(t + 2) * kstep; const char* b2 = last ? nB : cB + (size_t)(t + 2) * kstep;
;             const char* a3 = a2 + kstep; const char* b3 = b2 + kstep;
;             PG8_LDB(B0, 0, 0); PG8_LDB(B1, 0, 1); PG8_SCHED; PG8_LDA(At, 0, 0); PG8_STAGE(PG8_SA(1, 1), a1 + hstepA, voffA);
;             PG8_WAIT_V(8); PG8_WAIT_L(0); PG8_BAR; PG8_MMA(0, 0, At, B0); PG8_MMA(0, 1, At, B1); PG8_BAR; PG8_SCHED;
;             PG8_LDA(At, 0, 1); PG8_STAGE(PG8_SB(0, 0), b2, voffB); PG8_STAGE(PG8_SB(0, 1), b2 + hstepB, voffB); PG8_STAGE(PG8_SA(0, 0), a2, voffA);
;             PG8_WAIT_V(8); PG8_WAIT_L(0); PG8_BAR; PG8_MMA(1, 0, At, B0); PG8_MMA(1, 1, At, B1); PG8_BAR; PG8_SCHED;
.LBB0_1498:
	s_add_i32 m0, s13, 0xc000
	v_lshl_add_u64 v[200:201], s[46:47], 0, v[176:177]
	global_load_lds_dwordx4 v[200:201], off
	s_add_i32 m0, s13, 0xe000
	v_lshl_add_u64 v[200:201], s[46:47], 0, v[178:179]
	global_load_lds_dwordx4 v[200:201], off
	s_add_u32 s4, s46, 0x100
	s_addc_u32 s5, s47, 0
	s_add_i32 s30, 0, 0x10000
	s_cmpk_eq_i32 s29, 0x52
	s_cselect_b32 s59, s41, s5
	s_cselect_b32 s58, s40, s4
	s_cselect_b32 s7, s57, s28
	s_cselect_b32 s6, s56, s27
	s_add_i32 s34, 0, 0x14000
	v_add_u32_e32 v62, s30, v209
	v_add_u32_e32 v158, s34, v209
	ds_read_b128 v[50:53], v62
	ds_read_b128 v[54:57], v62 offset:1024
	ds_read_b128 v[58:61], v62 offset:2048
	ds_read_b128 v[62:65], v62 offset:3072
	ds_read_b128 v[146:149], v158
	ds_read_b128 v[150:153], v158 offset:1024
	ds_read_b128 v[154:157], v158 offset:2048
	ds_read_b128 v[158:161], v158 offset:3072
	ds_read_b128 v[162:165], v215
	ds_read_b128 v[166:169], v215 offset:1024
	ds_read_b128 v[170:173], v215 offset:2048
	ds_read_b128 v[180:183], v215 offset:3072
	ds_read_b128 v[184:187], v215 offset:4096
	ds_read_b128 v[188:191], v215 offset:5120
	ds_read_b128 v[192:195], v215 offset:6144
	ds_read_b128 v[196:199], v215 offset:7168
	s_setprio 1
	s_waitcnt vmcnt(8) lgkmcnt(0)
	s_barrier
	v_mfma_f32_16x16x32_bf16 v[142:145], v[50:53], v[162:165], v[142:145]
	v_mfma_f32_16x16x32_bf16 v[138:141], v[58:61], v[162:165], v[138:141]
	v_mfma_f32_16x16x32_bf16 v[126:129], v[50:53], v[170:173], v[126:129]
	v_mfma_f32_16x16x32_bf16 v[122:125], v[58:61], v[170:173], v[122:125]
	v_mfma_f32_16x16x32_bf16 v[110:113], v[50:53], v[184:187], v[110:113]
	v_mfma_f32_16x16x32_bf16 v[106:109], v[58:61], v[184:187], v[106:109]
	v_mfma_f32_16x16x32_bf16 v[94:97], v[50:53], v[192:195], v[94:97]
	v_mfma_f32_16x16x32_bf16 v[90:93], v[58:61], v[192:195], v[90:93]
	v_mfma_f32_16x16x32_bf16 v[142:145], v[54:57], v[166:169], v[142:145]
	v_mfma_f32_16x16x32_bf16 v[138:141], v[62:65], v[166:169], v[138:141]
	v_mfma_f32_16x16x32_bf16 v[126:129], v[54:57], v[180:183], v[126:129]
	v_mfma_f32_16x16x32_bf16 v[122:125], v[62:65], v[180:183], v[122:125]
	v_mfma_f32_16x16x32_bf16 v[110:113], v[54:57], v[188:191], v[110:113]
	v_mfma_f32_16x16x32_bf16 v[106:109], v[62:65], v[188:191], v[106:109]
	v_mfma_f32_16x16x32_bf16 v[94:97], v[54:57], v[196:199], v[94:97]
	v_mfma_f32_16x16x32_bf16 v[90:93], v[62:65], v[196:199], v[90:93]
	v_mfma_f32_16x16x32_bf16 v[134:137], v[146:149], v[162:165], v[134:137]
	v_mfma_f32_16x16x32_bf16 v[130:133], v[154:157], v[162:165], v[130:133]
	v_mfma_f32_16x16x32_bf16 v[118:121], v[146:149], v[170:173], v[118:121]
	v_mfma_f32_16x16x32_bf16 v[114:117], v[154:157], v[170:173], v[114:117]
	v_mfma_f32_16x16x32_bf16 v[102:105], v[146:149], v[184:187], v[102:105]
	v_mfma_f32_16x16x32_bf16 v[98:101], v[154:157], v[184:187], v[98:101]
	v_mfma_f32_16x16x32_bf16 v[86:89], v[146:149], v[192:195], v[86:89]
	v_mfma_f32_16x16x32_bf16 v[82:85], v[154:157], v[192:195], v[82:85]
	v_mfma_f32_16x16x32_bf16 v[134:137], v[150:153], v[166:169], v[134:137]
	v_mfma_f32_16x16x32_bf16 v[130:133], v[158:161], v[166:169], v[130:133]
	v_mfma_f32_16x16x32_bf16 v[118:121], v[150:153], v[180:183], v[118:121]
	v_mfma_f32_16x16x32_bf16 v[114:117], v[158:161], v[180:183], v[114:117]
	v_mfma_f32_16x16x32_bf16 v[102:105], v[150:153], v[188:191], v[102:105]
	v_mfma_f32_16x16x32_bf16 v[98:101], v[158:161], v[188:191], v[98:101]
	v_mfma_f32_16x16x32_bf16 v[86:89], v[150:153], v[196:199], v[86:89]
	v_mfma_f32_16x16x32_bf16 v[82:85], v[158:161], v[196:199], v[82:85]
	s_setprio 0
	s_barrier
	s_add_i32 s30, s30, s12
	s_mov_b32 m0, s30
	v_lshl_add_u64 v[200:201], s[6:7], 0, v[0:1]
	global_load_lds_dwordx4 v[200:201], off
	s_add_i32 m0, s30, 0x2000
	s_add_u32 s30, s6, 0x158000
	v_lshl_add_u64 v[202:203], s[6:7], 0, v[174:175]
	s_addc_u32 s31, s7, 0
	s_add_i32 s34, s34, s12
	global_load_lds_dwordx4 v[202:203], off
	v_lshl_add_u64 v[204:205], s[30:31], 0, v[0:1]
	s_mov_b32 m0, s34
	v_lshl_add_u64 v[206:207], s[58:59], 0, v[174:175]
	global_load_lds_dwordx4 v[204:205], off
	s_add_i32 m0, s34, 0x2000
	v_lshl_add_u64 v[204:205], s[30:31], 0, v[174:175]
	global_load_lds_dwordx4 v[204:205], off
	s_mov_b32 m0, s13
	v_lshl_add_u64 v[204:205], s[58:59], 0, v[0:1]
	global_load_lds_dwordx4 v[204:205], off
	s_mov_b32 m0, s24
	s_nop 0
	global_load_lds_dwordx4 v[206:207], off
	ds_read_b128 v[162:165], v215 offset:16384
	ds_read_b128 v[166:169], v215 offset:17408
	ds_read_b128 v[170:173], v215 offset:18432
	ds_read_b128 v[180:183], v215 offset:19456
	ds_read_b128 v[184:187], v215 offset:20480
	ds_read_b128 v[188:191], v215 offset:21504
	ds_read_b128 v[192:195], v215 offset:22528
	ds_read_b128 v[196:199], v215 offset:23552
	s_setprio 1
	s_waitcnt vmcnt(8) lgkmcnt(0)
	s_barrier
; #define PG8_STAGE(bufoff, gbase, voff) do { _Pragma("unroll") for (int _i = 0; _i < 2; ++_i) \
;         __builtin_amdgcn_global_load_lds((const unsigned*)((const char*)(gbase) + (voff)[_i]), (LAS unsigned*)(lds + (bufoff) + ldsw + _i * 8192), 16, 0, 0); } while (0)
; #define PG8_LDA(dst, b, h) do { _Pragma("unroll") for (int m = 0; m < 4; ++m) _Pragma("unroll") for (int k = 0; k < 2; ++k) dst[m][k] = *(const LAS bf16x8*)(lds + PG8_SA(b, h) + aoff + m * 2048 + k * 1024); } while (0)
; #define PG8_LDB(dst, b, h) do { _Pragma("unroll") for (int n = 0; n < 2; ++n) _Pragma("unroll") for (int k = 0; k < 2; ++k) dst[n][k] = *(const LAS bf16x8*)(lds + PG8_SB(b, h) + boff + n * 2048 + k * 1024); } while (0)
; #define PG8_MMA(ai, bj, At, Bt) do { __builtin_amdgcn_s_setprio(1); _Pragma("unroll") for (int m = 0; m < 4; ++m) _Pragma("unroll") for (int n = 0; n < 2; ++n) _Pragma("unroll") for (int k = 0; k < 2; ++k) \
;         acc[ai][bj][m][n] = __builtin_amdgcn_mfma_f32_16x16x32_bf16(Bt[n][k], At[m][k], acc[ai][bj][m][n], 0, 0, 0); __builtin_amdgcn_s_setprio(0); } while (0)
; #define PG8_WAIT_V(n) asm volatile("s_waitcnt vmcnt(" #n ")" ::: "memory")
; #define PG8_WAIT_L(n) asm volatile("s_waitcnt lgkmcnt(" #n ")" ::: "memory")
; #define PG8_BAR __builtin_amdgcn_s_barrier()
; #define PG8_SCHED __builtin_amdgcn_sched_barrier(0)
; template <class Epi, int AMODE>
; __device__ __forceinline__ void gemm_phase(LAS unsigned char* lds, const Gemm g, const StaticOrder& S, const Epi& E, int stagger_us, int tid_in) {
;     ...
;             PG8_WAIT_V(8); PG8_WAIT_L(0); PG8_BAR; PG8_MMA(1, 0, At, B0); PG8_MMA(1, 1, At, B1); PG8_BAR; PG8_SCHED;
;             PG8_LDB(B0, 1, 0); PG8_LDB(B1, 1, 1); PG8_SCHED; PG8_LDA(At, 1, 0); PG8_STAGE(PG8_SA(0, 1), a2 + hstepA, voffA);
;             PG8_WAIT_V(8); PG8_WAIT_L(0); PG8_BAR; PG8_MMA(0, 0, At, B0); PG8_MMA(0, 1, At, B1); PG8_BAR; PG8_SCHED;
	v_mfma_f32_16x16x32_bf16 v[78:81], v[50:53], v[162:165], v[78:81]
	v_mfma_f32_16x16x32_bf16 v[74:77], v[58:61], v[162:165], v[74:77]
	v_mfma_f32_16x16x32_bf16 v[46:49], v[50:53], v[170:173], v[46:49]
	v_mfma_f32_16x16x32_bf16 v[42:45], v[58:61], v[170:173], v[42:45]
	v_mfma_f32_16x16x32_bf16 v[30:33], v[50:53], v[184:187], v[30:33]
	v_mfma_f32_16x16x32_bf16 v[26:29], v[58:61], v[184:187], v[26:29]
	v_mfma_f32_16x16x32_bf16 v[14:17], v[50:53], v[192:195], v[14:17]
	v_mfma_f32_16x16x32_bf16 v[10:13], v[58:61], v[192:195], v[10:13]
	v_mfma_f32_16x16x32_bf16 v[78:81], v[54:57], v[166:169], v[78:81]
	v_mfma_f32_16x16x32_bf16 v[74:77], v[62:65], v[166:169], v[74:77]
	v_mfma_f32_16x16x32_bf16 v[46:49], v[54:57], v[180:183], v[46:49]
	v_mfma_f32_16x16x32_bf16 v[42:45], v[62:65], v[180:183], v[42:45]
	v_mfma_f32_16x16x32_bf16 v[30:33], v[54:57], v[188:191], v[30:33]
	v_mfma_f32_16x16x32_bf16 v[26:29], v[62:65], v[188:191], v[26:29]
	v_mfma_f32_16x16x32_bf16 v[14:17], v[54:57], v[196:199], v[14:17]
	v_mfma_f32_16x16x32_bf16 v[10:13], v[62:65], v[196:199], v[10:13]
	v_mfma_f32_16x16x32_bf16 v[38:41], v[146:149], v[170:173], v[38:41]
	v_mfma_f32_16x16x32_bf16 v[34:37], v[154:157], v[170:173], v[34:37]
	v_mfma_f32_16x16x32_bf16 v[22:25], v[146:149], v[184:187], v[22:25]
	v_mfma_f32_16x16x32_bf16 v[18:21], v[154:157], v[184:187], v[18:21]
	v_mfma_f32_16x16x32_bf16 v[6:9], v[146:149], v[192:195], v[6:9]
	v_mfma_f32_16x16x32_bf16 v[2:5], v[154:157], v[192:195], v[2:5]
	v_mfma_f32_16x16x32_bf16 v[50:53], v[146:149], v[162:165], v[70:73]
	v_mfma_f32_16x16x32_bf16 v[54:57], v[154:157], v[162:165], v[66:69]
	v_mfma_f32_16x16x32_bf16 v[38:41], v[150:153], v[180:183], v[38:41]
	v_mfma_f32_16x16x32_bf16 v[34:37], v[158:161], v[180:183], v[34:37]
	v_mfma_f32_16x16x32_bf16 v[22:25], v[150:153], v[188:191], v[22:25]
	v_mfma_f32_16x16x32_bf16 v[18:21], v[158:161], v[188:191], v[18:21]
	v_mfma_f32_16x16x32_bf16 v[6:9], v[150:153], v[196:199], v[6:9]
	v_mfma_f32_16x16x32_bf16 v[2:5], v[158:161], v[196:199], v[2:5]
	v_mfma_f32_16x16x32_bf16 v[50:53], v[150:153], v[166:169], v[50:53]
	v_mfma_f32_16x16x32_bf16 v[54:57], v[158:161], v[166:169], v[54:57]
	s_setprio 0
	s_barrier
	s_add_u32 s30, s58, 0x158000
	s_addc_u32 s31, s59, 0
	s_mov_b32 m0, s25
	v_lshl_add_u64 v[210:211], s[30:31], 0, v[0:1]
	global_load_lds_dwordx4 v[210:211], off
	s_mov_b32 m0, s66
	v_lshl_add_u64 v[210:211], s[30:31], 0, v[174:175]
	global_load_lds_dwordx4 v[210:211], off
	s_add_i32 s34, 0, 0x18000
	s_add_i32 s35, 0, 0x1c000
	v_add_u32_e32 v70, s34, v209
	v_add_u32_e32 v158, s35, v209
	ds_read_b128 v[58:61], v70
	ds_read_b128 v[62:65], v70 offset:1024
	ds_read_b128 v[66:69], v70 offset:2048
	ds_read_b128 v[70:73], v70 offset:3072
	ds_read_b128 v[146:149], v158
	ds_read_b128 v[150:153], v158 offset:1024
	ds_read_b128 v[154:157], v158 offset:2048
	ds_read_b128 v[158:161], v158 offset:3072
	ds_read_b128 v[162:165], v215 offset:32768
	ds_read_b128 v[166:169], v215 offset:33792
	ds_read_b128 v[170:173], v215 offset:34816
	ds_read_b128 v[180:183], v215 offset:35840
	ds_read_b128 v[184:187], v215 offset:36864
	ds_read_b128 v[188:191], v215 offset:37888
	ds_read_b128 v[192:195], v215 offset:38912
	ds_read_b128 v[196:199], v215 offset:39936
	s_setprio 1
	s_waitcnt vmcnt(8) lgkmcnt(0)
	s_barrier
	v_mfma_f32_16x16x32_bf16 v[142:145], v[58:61], v[162:165], v[142:145]
	v_mfma_f32_16x16x32_bf16 v[138:141], v[66:69], v[162:165], v[138:141]
	v_mfma_f32_16x16x32_bf16 v[126:129], v[58:61], v[170:173], v[126:129]
	v_mfma_f32_16x16x32_bf16 v[122:125], v[66:69], v[170:173], v[122:125]
	v_mfma_f32_16x16x32_bf16 v[110:113], v[58:61], v[184:187], v[110:113]
	v_mfma_f32_16x16x32_bf16 v[106:109], v[66:69], v[184:187], v[106:109]
	v_mfma_f32_16x16x32_bf16 v[94:97], v[58:61], v[192:195], v[94:97]
	v_mfma_f32_16x16x32_bf16 v[90:93], v[66:69], v[192:195], v[90:93]
	v_mfma_f32_16x16x32_bf16 v[142:145], v[62:65], v[166:169], v[142:145]
	v_mfma_f32_16x16x32_bf16 v[138:141], v[70:73], v[166:169], v[138:141]
	v_mfma_f32_16x16x32_bf16 v[126:129], v[62:65], v[180:183], v[126:129]
	v_mfma_f32_16x16x32_bf16 v[122:125], v[70:73], v[180:183], v[122:125]
	v_mfma_f32_16x16x32_bf16 v[110:113], v[62:65], v[188:191], v[110:113]
	v_mfma_f32_16x16x32_bf16 v[106:109], v[70:73], v[188:191], v[106:109]
	v_mfma_f32_16x16x32_bf16 v[94:97], v[62:65], v[196:199], v[94:97]
	v_mfma_f32_16x16x32_bf16 v[90:93], v[70:73], v[196:199], v[90:93]
	v_mfma_f32_16x16x32_bf16 v[134:137], v[146:149], v[162:165], v[134:137]
	v_mfma_f32_16x16x32_bf16 v[130:133], v[154:157], v[162:165], v[130:133]
	v_mfma_f32_16x16x32_bf16 v[118:121], v[146:149], v[170:173], v[118:121]
	v_mfma_f32_16x16x32_bf16 v[114:117], v[154:157], v[170:173], v[114:117]
	v_mfma_f32_16x16x32_bf16 v[102:105], v[146:149], v[184:187], v[102:105]
	v_mfma_f32_16x16x32_bf16 v[98:101], v[154:157], v[184:187], v[98:101]
	v_mfma_f32_16x16x32_bf16 v[86:89], v[146:149], v[192:195], v[86:89]
	v_mfma_f32_16x16x32_bf16 v[82:85], v[154:157], v[192:195], v[82:85]
	v_mfma_f32_16x16x32_bf16 v[134:137], v[150:153], v[166:169], v[134:137]
	v_mfma_f32_16x16x32_bf16 v[130:133], v[158:161], v[166:169], v[130:133]
	v_mfma_f32_16x16x32_bf16 v[118:121], v[150:153], v[180:183], v[118:121]
	v_mfma_f32_16x16x32_bf16 v[114:117], v[158:161], v[180:183], v[114:117]
	v_mfma_f32_16x16x32_bf16 v[102:105], v[150:153], v[188:191], v[102:105]
	v_mfma_f32_16x16x32_bf16 v[98:101], v[158:161], v[188:191], v[98:101]
	v_mfma_f32_16x16x32_bf16 v[86:89], v[150:153], v[196:199], v[86:89]
	v_mfma_f32_16x16x32_bf16 v[82:85], v[158:161], v[196:199], v[82:85]
	s_setprio 0
	s_barrier
; #define PG8_STAGE(bufoff, gbase, voff) do { _Pragma("unroll") for (int _i = 0; _i < 2; ++_i) \
;         __builtin_amdgcn_global_load_lds((const unsigned*)((const char*)(gbase) + (voff)[_i]), (LAS unsigned*)(lds + (bufoff) + ldsw + _i * 8192), 16, 0, 0); } while (0)
; #define PG8_LDA(dst, b, h) do { _Pragma("unroll") for (int m = 0; m < 4; ++m) _Pragma("unroll") for (int k = 0; k < 2; ++k) dst[m][k] = *(const LAS bf16x8*)(lds + PG8_SA(b, h) + aoff + m * 2048 + k * 1024); } while (0)
; #define PG8_MMA(ai, bj, At, Bt) do { __builtin_amdgcn_s_setprio(1); _Pragma("unroll") for (int m = 0; m < 4; ++m) _Pragma("unroll") for (int n = 0; n < 2; ++n) _Pragma("unroll") for (int k = 0; k < 2; ++k) \
;         acc[ai][bj][m][n] = __builtin_amdgcn_mfma_f32_16x16x32_bf16(Bt[n][k], At[m][k], acc[ai][bj][m][n], 0, 0, 0); __builtin_amdgcn_s_setprio(0); } while (0)
; #define PG8_WAIT_V(n) asm volatile("s_waitcnt vmcnt(" #n ")" ::: "memory")
; #define PG8_WAIT_L(n) asm volatile("s_waitcnt lgkmcnt(" #n ")" ::: "memory")
; #define PG8_BAR __builtin_amdgcn_s_barrier()
; #define PG8_SCHED __builtin_amdgcn_sched_barrier(0)
; template <class Epi, int AMODE>
; __device__ __forceinline__ void gemm_phase(LAS unsigned char* lds, const Gemm g, const StaticOrder& S, const Epi& E, int stagger_us, int tid_in) {
;     ...
;             PG8_LDA(At, 1, 1); PG8_STAGE(PG8_SB(1, 0), b3, voffB); PG8_STAGE(PG8_SB(1, 1), b3 + hstepB, voffB); PG8_STAGE(PG8_SA(1, 0), a3, voffA);
;             PG8_WAIT_V(8); PG8_WAIT_L(0); PG8_BAR; PG8_MMA(1, 0, At, B0); PG8_MMA(1, 1, At, B1); PG8_BAR; PG8_SCHED;
;         }
	s_add_i32 s30, s34, s12
	s_mov_b32 m0, s30
	v_lshl_add_u64 v[200:201], v[200:201], 0, s[74:75]
	global_load_lds_dwordx4 v[200:201], off
	s_add_i32 m0, s30, 0x2000
	s_add_u32 s6, s6, 0x158080
	v_lshl_add_u64 v[200:201], v[202:203], 0, s[74:75]
	s_addc_u32 s7, s7, 0
	s_add_i32 s30, s35, s12
	global_load_lds_dwordx4 v[200:201], off
	s_mov_b32 m0, s30
	v_lshl_add_u64 v[200:201], s[6:7], 0, v[0:1]
	global_load_lds_dwordx4 v[200:201], off
	s_add_i32 m0, s30, 0x2000
	v_lshl_add_u64 v[200:201], s[6:7], 0, v[174:175]
	global_load_lds_dwordx4 v[200:201], off
	s_mov_b32 m0, s79
	v_lshl_add_u64 v[200:201], v[204:205], 0, s[74:75]
	global_load_lds_dwordx4 v[200:201], off
	s_mov_b32 m0, s83
	v_lshl_add_u64 v[200:201], v[206:207], 0, s[74:75]
	global_load_lds_dwordx4 v[200:201], off
	ds_read_b128 v[162:165], v215 offset:49152
	ds_read_b128 v[166:169], v215 offset:50176
	ds_read_b128 v[170:173], v215 offset:51200
	ds_read_b128 v[180:183], v215 offset:52224
	ds_read_b128 v[184:187], v215 offset:53248
	ds_read_b128 v[188:191], v215 offset:54272
	ds_read_b128 v[192:195], v215 offset:55296
	ds_read_b128 v[196:199], v215 offset:56320
	s_setprio 1
	s_waitcnt vmcnt(8) lgkmcnt(0)
	s_barrier
	v_mfma_f32_16x16x32_bf16 v[78:81], v[58:61], v[162:165], v[78:81]
	v_mfma_f32_16x16x32_bf16 v[74:77], v[66:69], v[162:165], v[74:77]
	v_mfma_f32_16x16x32_bf16 v[46:49], v[58:61], v[170:173], v[46:49]
	v_mfma_f32_16x16x32_bf16 v[42:45], v[66:69], v[170:173], v[42:45]
	v_mfma_f32_16x16x32_bf16 v[30:33], v[58:61], v[184:187], v[30:33]
	v_mfma_f32_16x16x32_bf16 v[26:29], v[66:69], v[184:187], v[26:29]
	v_mfma_f32_16x16x32_bf16 v[14:17], v[58:61], v[192:195], v[14:17]
	v_mfma_f32_16x16x32_bf16 v[10:13], v[66:69], v[192:195], v[10:13]
	v_mfma_f32_16x16x32_bf16 v[78:81], v[62:65], v[166:169], v[78:81]
	v_mfma_f32_16x16x32_bf16 v[74:77], v[70:73], v[166:169], v[74:77]
	v_mfma_f32_16x16x32_bf16 v[46:49], v[62:65], v[180:183], v[46:49]
	v_mfma_f32_16x16x32_bf16 v[42:45], v[70:73], v[180:183], v[42:45]
	v_mfma_f32_16x16x32_bf16 v[30:33], v[62:65], v[188:191], v[30:33]
	v_mfma_f32_16x16x32_bf16 v[26:29], v[70:73], v[188:191], v[26:29]
	v_mfma_f32_16x16x32_bf16 v[14:17], v[62:65], v[196:199], v[14:17]
	v_mfma_f32_16x16x32_bf16 v[10:13], v[70:73], v[196:199], v[10:13]
	v_mfma_f32_16x16x32_bf16 v[50:53], v[146:149], v[162:165], v[50:53]
	v_mfma_f32_16x16x32_bf16 v[70:73], v[150:153], v[166:169], v[50:53]
	v_mfma_f32_16x16x32_bf16 v[50:53], v[154:157], v[162:165], v[54:57]
	v_mfma_f32_16x16x32_bf16 v[38:41], v[146:149], v[170:173], v[38:41]
	v_mfma_f32_16x16x32_bf16 v[34:37], v[154:157], v[170:173], v[34:37]
	v_mfma_f32_16x16x32_bf16 v[22:25], v[146:149], v[184:187], v[22:25]
	v_mfma_f32_16x16x32_bf16 v[18:21], v[154:157], v[184:187], v[18:21]
	v_mfma_f32_16x16x32_bf16 v[6:9], v[146:149], v[192:195], v[6:9]
	v_mfma_f32_16x16x32_bf16 v[2:5], v[154:157], v[192:195], v[2:5]
	v_mfma_f32_16x16x32_bf16 v[66:69], v[158:161], v[166:169], v[50:53]
	v_mfma_f32_16x16x32_bf16 v[38:41], v[150:153], v[180:183], v[38:41]
	v_mfma_f32_16x16x32_bf16 v[34:37], v[158:161], v[180:183], v[34:37]
	v_mfma_f32_16x16x32_bf16 v[22:25], v[150:153], v[188:191], v[22:25]
	v_mfma_f32_16x16x32_bf16 v[18:21], v[158:161], v[188:191], v[18:21]
	v_mfma_f32_16x16x32_bf16 v[6:9], v[150:153], v[196:199], v[6:9]
	v_mfma_f32_16x16x32_bf16 v[2:5], v[158:161], v[196:199], v[2:5]
	s_setprio 0
	s_barrier
	s_add_i32 s29, s29, 2
	s_add_u32 s27, s27, 0x100
	s_addc_u32 s28, s28, 0
	s_cmpk_gt_u32 s29, 0x53
	s_mov_b64 s[46:47], s[4:5]
	s_cbranch_scc0 .LBB0_1498
	s_and_b64 vcc, exec, s[54:55]
	s_cbranch_vccz .LBB0_1501
	s_barrier
